# M1c hand-rewritten (LDS-write data hazard fixed with lgkmcnt wait before reusing registers)
# speedup vs baseline: 1.0030x; 1.0030x over previous
; DI float gelu_f(float x) { return x * __builtin_amdgcn_rcpf(1.f + __builtin_amdgcn_exp2f(x * (-2.302208198f + -0.102943240f * (x * x)))); }
; __global__ void __launch_bounds__(512, 2) fwd_megakernel(Args args) {
;     ...
;                 const int l = tid >> 2, sub = tid & 3;
;                 u32x4 gvr[8], ur[8]; bf16x8 wa[4][4];
;                 {
;                     const bf16* src = proj + (grow0 + l) * NPROJ + PC_GV + sub * 64;
; #pragma unroll
;                     for (int k = 0; k < 8; ++k) gvr[k] = *(const u32x4*)(src + 8 * k);
; #pragma unroll
;                     for (int k = 0; k < 8; ++k) { const int it = tid + 512 * k, t = it >> 5, c8 = (it & 31) * 8; ur[k] = *(const u32x4*)(proj + (grow0 + t) * NPROJ + PC_U + c8); }
;                 }
;                 {
;                     float v[64]; float sm = 0.f;
; #pragma unroll
;                     for (int k = 0; k < 8; ++k) { float t8[8]; unpack8(gvr[k], t8);
; #pragma unroll
;                         for (int i = 0; i < 8; ++i) { v[8 * k + i] = gelu_f(t8[i]); sm += v[8 * k + i]; } }
.LBB0_800:
	s_waitcnt vmcnt(0) lgkmcnt(0)
	v_readlane_b32 s2, v252, 0
	s_and_b32 s3, s54, 7
	s_lshl_b32 s3, s3, 5
	s_lshr_b32 s4, s54, 3
	s_add_i32 s3, s3, s4
	s_mul_i32 s4, s3, 0xb0000
	s_add_u32 s8, s80, 0x15000000
	s_addc_u32 s9, s81, 0
	s_add_u32 s8, s8, s4
	s_addc_u32 s9, s9, 0
	s_lshl_b32 s4, s3, 18
	s_add_u32 s10, s80, 0xe000600
	s_addc_u32 s11, s81, 0
	s_add_u32 s10, s10, s4
	s_addc_u32 s11, s11, 0
	v_readlane_b32 s5, v253, 58
	s_lshl_b32 s6, s5, 14
	s_add_u32 s12, s80, 0x600000
	s_addc_u32 s13, s81, 0
	s_add_u32 s12, s12, s6
	s_addc_u32 s13, s13, 0
	s_lshl_b32 s6, s5, 7
	v_readlane_b32 s14, v251, 41
	v_readlane_b32 s15, v251, 42
	s_add_u32 s14, s14, s6
	s_addc_u32 s15, s15, 0
	v_readlane_b32 s22, v251, 43
	v_readlane_b32 s23, v251, 44
	s_add_u32 s22, s22, s6
	s_addc_u32 s23, s23, 0
	v_readlane_b32 s24, v251, 49
	v_readlane_b32 s25, v251, 50
	s_add_u32 s24, s24, s6
	s_addc_u32 s25, s25, 0
	s_lshl_b32 s6, s5, 8
	v_readlane_b32 s36, v251, 47
	v_readlane_b32 s37, v251, 48
	s_add_u32 s36, s36, s6
	s_addc_u32 s37, s37, 0
	v_and_b32_e32 v184, 63, v195
	v_and_b32_e32 v185, 15, v184
	v_lshrrev_b32_e32 v186, 4, v184
	v_lshl_add_u32 v187, s2, 4, v185
	v_lshlrev_b32_e32 v196, 2, v186
	v_lshl_add_u32 v196, s2, 4, v196
	v_mul_u32_u24_e32 v188, 0x1600, v196
	v_lshl_add_u32 v188, v185, 5, v188
	v_add_u32_e32 v188, 0x1200, v188
	global_load_dwordx4 v[0:3], v188, s[8:9]
	global_load_dwordx4 v[4:7], v188, s[8:9] offset:16
	v_add_u32_e32 v188, 0x1600, v188
	global_load_dwordx4 v[8:11], v188, s[8:9]
	global_load_dwordx4 v[12:15], v188, s[8:9] offset:16
	v_add_u32_e32 v188, 0x1600, v188
	global_load_dwordx4 v[16:19], v188, s[8:9]
	global_load_dwordx4 v[20:23], v188, s[8:9] offset:16
	v_add_u32_e32 v188, 0x1600, v188
	global_load_dwordx4 v[24:27], v188, s[8:9]
	global_load_dwordx4 v[28:31], v188, s[8:9] offset:16
	v_lshlrev_b32_e32 v188, 6, v185
	global_load_dwordx4 v[32:35], v188, s[14:15] offset:0
	global_load_dwordx4 v[48:51], v188, s[22:23] offset:0
	global_load_dwordx4 v[36:39], v188, s[14:15] offset:16
	global_load_dwordx4 v[52:55], v188, s[22:23] offset:16
	global_load_dwordx4 v[40:43], v188, s[14:15] offset:32
	global_load_dwordx4 v[56:59], v188, s[22:23] offset:32
	global_load_dwordx4 v[44:47], v188, s[14:15] offset:48
	global_load_dwordx4 v[60:63], v188, s[22:23] offset:48
	v_mul_u32_u24_e32 v188, 0x1600, v187
	v_lshl_add_u32 v188, v186, 3, v188
	v_add_u32_e32 v188, 0x1000, v188
	global_load_dwordx2 v[148:149], v188, s[8:9] offset:0
	global_load_dwordx2 v[150:151], v188, s[8:9] offset:32
	global_load_dwordx2 v[152:153], v188, s[8:9] offset:64
	global_load_dwordx2 v[154:155], v188, s[8:9] offset:96
	global_load_dwordx2 v[156:157], v188, s[8:9] offset:128
	global_load_dwordx2 v[158:159], v188, s[8:9] offset:160
	global_load_dwordx2 v[160:161], v188, s[8:9] offset:192
	global_load_dwordx2 v[162:163], v188, s[8:9] offset:224
	global_load_dwordx2 v[164:165], v188, s[8:9] offset:256
	global_load_dwordx2 v[166:167], v188, s[8:9] offset:288
	global_load_dwordx2 v[168:169], v188, s[8:9] offset:320
	global_load_dwordx2 v[170:171], v188, s[8:9] offset:352
	global_load_dwordx2 v[172:173], v188, s[8:9] offset:384
	global_load_dwordx2 v[174:175], v188, s[8:9] offset:416
	global_load_dwordx2 v[176:177], v188, s[8:9] offset:448
	global_load_dwordx2 v[178:179], v188, s[8:9] offset:480
	v_lshlrev_b32_e32 v188, 2, v187
	global_load_dword v180, v188, s[36:37] offset:0
	global_load_dword v181, v188, s[36:37] offset:512
	global_load_dword v182, v188, s[36:37] offset:1024
	global_load_dword v183, v188, s[36:37] offset:1536
	v_lshrrev_b32_e32 v189, 2, v185
	v_mul_u32_u24_e32 v189, 0x4400, v189
	v_and_b32_e32 v188, 3, v185
	v_mul_u32_u24_e32 v188, 0x1100, v188
	v_add_u32_e32 v189, v189, v188
	v_lshl_add_u32 v189, v196, 1, v189
	v_mov_b32_e32 v190, 0xc0135761
	v_mov_b32_e32 v191, 0xbdd2d3e8
	s_waitcnt vmcnt(20)
	v_lshlrev_b32_e32 v64, 16, v0
	v_and_b32_e32 v65, 0xffff0000, v0
	v_lshlrev_b32_e32 v66, 16, v1
	v_and_b32_e32 v67, 0xffff0000, v1
	v_lshlrev_b32_e32 v68, 16, v2
	v_and_b32_e32 v69, 0xffff0000, v2
	v_lshlrev_b32_e32 v70, 16, v3
	v_and_b32_e32 v71, 0xffff0000, v3
	v_lshlrev_b32_e32 v72, 16, v4
	v_and_b32_e32 v73, 0xffff0000, v4
	v_lshlrev_b32_e32 v74, 16, v5
	v_and_b32_e32 v75, 0xffff0000, v5
	v_lshlrev_b32_e32 v76, 16, v6
	v_and_b32_e32 v77, 0xffff0000, v6
	v_lshlrev_b32_e32 v78, 16, v7
	v_and_b32_e32 v79, 0xffff0000, v7
	v_mul_f32_e32 v132, v64, v64
	v_mul_f32_e32 v133, v65, v65
	v_mul_f32_e32 v134, v66, v66
	v_mul_f32_e32 v135, v67, v67
	v_mul_f32_e32 v136, v68, v68
	v_mul_f32_e32 v137, v69, v69
	v_mul_f32_e32 v138, v70, v70
	v_mul_f32_e32 v139, v71, v71
	v_mul_f32_e32 v140, v72, v72
	v_mul_f32_e32 v141, v73, v73
	v_mul_f32_e32 v142, v74, v74
	v_mul_f32_e32 v143, v75, v75
	v_mul_f32_e32 v144, v76, v76
	v_mul_f32_e32 v145, v77, v77
	v_mul_f32_e32 v146, v78, v78
	v_mul_f32_e32 v147, v79, v79
	v_fma_f32 v132, v132, v191, v190
	v_fma_f32 v133, v133, v191, v190
	v_fma_f32 v134, v134, v191, v190
	v_fma_f32 v135, v135, v191, v190
	v_fma_f32 v136, v136, v191, v190
	v_fma_f32 v137, v137, v191, v190
	v_fma_f32 v138, v138, v191, v190
	v_fma_f32 v139, v139, v191, v190
	v_fma_f32 v140, v140, v191, v190
	v_fma_f32 v141, v141, v191, v190
	v_fma_f32 v142, v142, v191, v190
	v_fma_f32 v143, v143, v191, v190
	v_fma_f32 v144, v144, v191, v190
	v_fma_f32 v145, v145, v191, v190
	v_fma_f32 v146, v146, v191, v190
	v_fma_f32 v147, v147, v191, v190
	v_mul_f32_e32 v132, v132, v64
	v_mul_f32_e32 v133, v133, v65
	v_mul_f32_e32 v134, v134, v66
	v_mul_f32_e32 v135, v135, v67
	v_mul_f32_e32 v136, v136, v68
	v_mul_f32_e32 v137, v137, v69
	v_mul_f32_e32 v138, v138, v70
	v_mul_f32_e32 v139, v139, v71
; #define LAS __attribute__((address_space(3)))
; DI unsigned short f2bf(float f) { return (unsigned short)(pk2(f, 0.f) & 0xffffu); }
; DI float gelu_f(float x) { return x * __builtin_amdgcn_rcpf(1.f + __builtin_amdgcn_exp2f(x * (-2.302208198f + -0.102943240f * (x * x)))); }
; __global__ void __launch_bounds__(512, 2) fwd_megakernel(Args args) {
;     ...
;                     float v[64]; float sm = 0.f;
; #pragma unroll
;                     for (int k = 0; k < 8; ++k) { float t8[8]; unpack8(gvr[k], t8);
; #pragma unroll
;                         for (int i = 0; i < 8; ++i) { v[8 * k + i] = gelu_f(t8[i]); sm += v[8 * k + i]; } }
;                     sm += __shfl_xor(sm, 1); sm += __shfl_xor(sm, 2);
;                     const float mean = sm * (1.f / 256.f); float qv = 0.f;
; #pragma unroll
;                     for (int i = 0; i < 64; ++i) { const float d = v[i] - mean; qv += d * d; }
;                     qv += __shfl_xor(qv, 1); qv += __shfl_xor(qv, 2);
;                     const float rstd = rsqrtf(qv * (1.f / 256.f) + EPS);
;                     const float* lw = args.in[16] + layer * 256 + sub * 64; const float* lb = args.in[17] + layer * 256 + sub * 64;
;                     LAS bf16* dst = vnT + sub * (64 * 136) + l;
; #pragma unroll
;                     for (int i = 0; i < 64; ++i) dst[i * 136] = f2bf((v[i] - mean) * rstd * lw[i] + lb[i]);
	v_mul_f32_e32 v140, v140, v72
	v_mul_f32_e32 v141, v141, v73
	v_mul_f32_e32 v142, v142, v74
	v_mul_f32_e32 v143, v143, v75
	v_mul_f32_e32 v144, v144, v76
	v_mul_f32_e32 v145, v145, v77
	v_mul_f32_e32 v146, v146, v78
	v_mul_f32_e32 v147, v147, v79
	v_exp_f32_e32 v132, v132
	v_exp_f32_e32 v133, v133
	v_exp_f32_e32 v134, v134
	v_exp_f32_e32 v135, v135
	v_exp_f32_e32 v136, v136
	v_exp_f32_e32 v137, v137
	v_exp_f32_e32 v138, v138
	v_exp_f32_e32 v139, v139
	v_exp_f32_e32 v140, v140
	v_exp_f32_e32 v141, v141
	v_exp_f32_e32 v142, v142
	v_exp_f32_e32 v143, v143
	v_exp_f32_e32 v144, v144
	v_exp_f32_e32 v145, v145
	v_exp_f32_e32 v146, v146
	v_exp_f32_e32 v147, v147
	s_nop 0
	v_add_f32_e32 v132, 1.0, v132
	v_add_f32_e32 v133, 1.0, v133
	v_add_f32_e32 v134, 1.0, v134
	v_add_f32_e32 v135, 1.0, v135
	v_add_f32_e32 v136, 1.0, v136
	v_add_f32_e32 v137, 1.0, v137
	v_add_f32_e32 v138, 1.0, v138
	v_add_f32_e32 v139, 1.0, v139
	v_add_f32_e32 v140, 1.0, v140
	v_add_f32_e32 v141, 1.0, v141
	v_add_f32_e32 v142, 1.0, v142
	v_add_f32_e32 v143, 1.0, v143
	v_add_f32_e32 v144, 1.0, v144
	v_add_f32_e32 v145, 1.0, v145
	v_add_f32_e32 v146, 1.0, v146
	v_add_f32_e32 v147, 1.0, v147
	v_rcp_f32_e32 v132, v132
	v_rcp_f32_e32 v133, v133
	v_rcp_f32_e32 v134, v134
	v_rcp_f32_e32 v135, v135
	v_rcp_f32_e32 v136, v136
	v_rcp_f32_e32 v137, v137
	v_rcp_f32_e32 v138, v138
	v_rcp_f32_e32 v139, v139
	v_rcp_f32_e32 v140, v140
	v_rcp_f32_e32 v141, v141
	v_rcp_f32_e32 v142, v142
	v_rcp_f32_e32 v143, v143
	v_rcp_f32_e32 v144, v144
	v_rcp_f32_e32 v145, v145
	v_rcp_f32_e32 v146, v146
	v_rcp_f32_e32 v147, v147
	s_nop 0
	v_mul_f32_e32 v64, v64, v132
	v_mul_f32_e32 v65, v65, v133
	v_mul_f32_e32 v66, v66, v134
	v_mul_f32_e32 v67, v67, v135
	v_mul_f32_e32 v68, v68, v136
	v_mul_f32_e32 v69, v69, v137
	v_mul_f32_e32 v70, v70, v138
	v_mul_f32_e32 v71, v71, v139
	v_mul_f32_e32 v72, v72, v140
	v_mul_f32_e32 v73, v73, v141
	v_mul_f32_e32 v74, v74, v142
	v_mul_f32_e32 v75, v75, v143
	v_mul_f32_e32 v76, v76, v144
	v_mul_f32_e32 v77, v77, v145
	v_mul_f32_e32 v78, v78, v146
	v_mul_f32_e32 v79, v79, v147
	v_add_f32_e32 v132, v64, v65
	v_add_f32_e32 v132, v132, v66
	v_add_f32_e32 v132, v132, v67
	v_add_f32_e32 v132, v132, v68
	v_add_f32_e32 v132, v132, v69
	v_add_f32_e32 v132, v132, v70
	v_add_f32_e32 v132, v132, v71
	v_add_f32_e32 v132, v132, v72
	v_add_f32_e32 v132, v132, v73
	v_add_f32_e32 v132, v132, v74
	v_add_f32_e32 v132, v132, v75
	v_add_f32_e32 v132, v132, v76
	v_add_f32_e32 v132, v132, v77
	v_add_f32_e32 v132, v132, v78
	v_add_f32_e32 v132, v132, v79
	s_nop 1
	v_add_f32_dpp v132, v132, v132 quad_perm:[1,0,3,2] row_mask:0xf bank_mask:0xf
	s_nop 1
	v_add_f32_dpp v132, v132, v132 quad_perm:[2,3,0,1] row_mask:0xf bank_mask:0xf
	s_nop 1
	v_add_f32_dpp v132, v132, v132 row_half_mirror row_mask:0xf bank_mask:0xf
	s_nop 1
	v_add_f32_dpp v132, v132, v132 row_mirror row_mask:0xf bank_mask:0xf
	s_nop 1
	v_mul_f32_e32 v132, 0x3b800000, v132
	v_sub_f32_e32 v64, v64, v132
	v_sub_f32_e32 v65, v65, v132
	v_sub_f32_e32 v66, v66, v132
	v_sub_f32_e32 v67, v67, v132
	v_sub_f32_e32 v68, v68, v132
	v_sub_f32_e32 v69, v69, v132
	v_sub_f32_e32 v70, v70, v132
	v_sub_f32_e32 v71, v71, v132
	v_sub_f32_e32 v72, v72, v132
	v_sub_f32_e32 v73, v73, v132
	v_sub_f32_e32 v74, v74, v132
	v_sub_f32_e32 v75, v75, v132
	v_sub_f32_e32 v76, v76, v132
	v_sub_f32_e32 v77, v77, v132
	v_sub_f32_e32 v78, v78, v132
	v_sub_f32_e32 v79, v79, v132
	v_mul_f32_e32 v133, v64, v64
	v_fmac_f32_e32 v133, v65, v65
	v_fmac_f32_e32 v133, v66, v66
	v_fmac_f32_e32 v133, v67, v67
	v_fmac_f32_e32 v133, v68, v68
	v_fmac_f32_e32 v133, v69, v69
	v_fmac_f32_e32 v133, v70, v70
	v_fmac_f32_e32 v133, v71, v71
	v_fmac_f32_e32 v133, v72, v72
	v_fmac_f32_e32 v133, v73, v73
	v_fmac_f32_e32 v133, v74, v74
	v_fmac_f32_e32 v133, v75, v75
	v_fmac_f32_e32 v133, v76, v76
	v_fmac_f32_e32 v133, v77, v77
	v_fmac_f32_e32 v133, v78, v78
	v_fmac_f32_e32 v133, v79, v79
	s_nop 1
	v_add_f32_dpp v133, v133, v133 quad_perm:[1,0,3,2] row_mask:0xf bank_mask:0xf
	s_nop 1
	v_add_f32_dpp v133, v133, v133 quad_perm:[2,3,0,1] row_mask:0xf bank_mask:0xf
	s_nop 1
	v_add_f32_dpp v133, v133, v133 row_half_mirror row_mask:0xf bank_mask:0xf
	s_nop 1
	v_add_f32_dpp v133, v133, v133 row_mirror row_mask:0xf bank_mask:0xf
	s_nop 1
	v_mov_b32_e32 v134, 0x358637bd
	v_fmamk_f32 v133, v133, 0x3b800000, v134
	v_rsq_f32_e32 v133, v133
	s_nop 0
	v_mul_f32_e32 v64, v64, v133
	v_mul_f32_e32 v65, v65, v133
	v_mul_f32_e32 v66, v66, v133
	v_mul_f32_e32 v67, v67, v133
	v_mul_f32_e32 v68, v68, v133
	v_mul_f32_e32 v69, v69, v133
	v_mul_f32_e32 v70, v70, v133
	v_mul_f32_e32 v71, v71, v133
	v_mul_f32_e32 v72, v72, v133
	v_mul_f32_e32 v73, v73, v133
	v_mul_f32_e32 v74, v74, v133
	v_mul_f32_e32 v75, v75, v133
	v_mul_f32_e32 v76, v76, v133
	v_mul_f32_e32 v77, v77, v133
	v_mul_f32_e32 v78, v78, v133
	v_mul_f32_e32 v79, v79, v133
	v_fma_f32 v64, v64, v32, v48
	v_fma_f32 v65, v65, v33, v49
	v_fma_f32 v66, v66, v34, v50
	v_fma_f32 v67, v67, v35, v51
	v_fma_f32 v68, v68, v36, v52
	v_fma_f32 v69, v69, v37, v53
	v_fma_f32 v70, v70, v38, v54
	v_fma_f32 v71, v71, v39, v55
	v_fma_f32 v72, v72, v40, v56
	v_fma_f32 v73, v73, v41, v57
	v_fma_f32 v74, v74, v42, v58
	v_fma_f32 v75, v75, v43, v59
	v_fma_f32 v76, v76, v44, v60
	v_fma_f32 v77, v77, v45, v61
	v_fma_f32 v78, v78, v46, v62
	v_fma_f32 v79, v79, v47, v63
	v_lshlrev_b32_e32 v80, 16, v8
	v_and_b32_e32 v81, 0xffff0000, v8
	v_lshlrev_b32_e32 v82, 16, v9
	v_and_b32_e32 v83, 0xffff0000, v9
	v_lshlrev_b32_e32 v84, 16, v10
	v_and_b32_e32 v85, 0xffff0000, v10
	v_lshlrev_b32_e32 v86, 16, v11
	v_and_b32_e32 v87, 0xffff0000, v11
	v_lshlrev_b32_e32 v92, 16, v12
	v_and_b32_e32 v93, 0xffff0000, v12
; #define LAS __attribute__((address_space(3)))
; DI unsigned short f2bf(float f) { return (unsigned short)(pk2(f, 0.f) & 0xffffu); }
; DI float gelu_f(float x) { return x * __builtin_amdgcn_rcpf(1.f + __builtin_amdgcn_exp2f(x * (-2.302208198f + -0.102943240f * (x * x)))); }
; __global__ void __launch_bounds__(512, 2) fwd_megakernel(Args args) {
;     ...
;                     float v[64]; float sm = 0.f;
; #pragma unroll
;                     for (int k = 0; k < 8; ++k) { float t8[8]; unpack8(gvr[k], t8);
; #pragma unroll
;                         for (int i = 0; i < 8; ++i) { v[8 * k + i] = gelu_f(t8[i]); sm += v[8 * k + i]; } }
;                     sm += __shfl_xor(sm, 1); sm += __shfl_xor(sm, 2);
;                     const float mean = sm * (1.f / 256.f); float qv = 0.f;
; #pragma unroll
;                     for (int i = 0; i < 64; ++i) { const float d = v[i] - mean; qv += d * d; }
;                     qv += __shfl_xor(qv, 1); qv += __shfl_xor(qv, 2);
;                     const float rstd = rsqrtf(qv * (1.f / 256.f) + EPS);
;                     const float* lw = args.in[16] + layer * 256 + sub * 64; const float* lb = args.in[17] + layer * 256 + sub * 64;
;                     LAS bf16* dst = vnT + sub * (64 * 136) + l;
; #pragma unroll
;                     for (int i = 0; i < 64; ++i) dst[i * 136] = f2bf((v[i] - mean) * rstd * lw[i] + lb[i]);
	v_lshlrev_b32_e32 v94, 16, v13
	v_and_b32_e32 v95, 0xffff0000, v13
	v_lshlrev_b32_e32 v96, 16, v14
	v_and_b32_e32 v97, 0xffff0000, v14
	v_lshlrev_b32_e32 v98, 16, v15
	v_and_b32_e32 v99, 0xffff0000, v15
	v_mul_f32_e32 v132, v80, v80
	v_mul_f32_e32 v133, v81, v81
	v_mul_f32_e32 v134, v82, v82
	v_mul_f32_e32 v135, v83, v83
	v_mul_f32_e32 v136, v84, v84
	v_mul_f32_e32 v137, v85, v85
	v_mul_f32_e32 v138, v86, v86
	v_mul_f32_e32 v139, v87, v87
	v_mul_f32_e32 v140, v92, v92
	v_mul_f32_e32 v141, v93, v93
	v_mul_f32_e32 v142, v94, v94
	v_mul_f32_e32 v143, v95, v95
	v_mul_f32_e32 v144, v96, v96
	v_mul_f32_e32 v145, v97, v97
	v_mul_f32_e32 v146, v98, v98
	v_mul_f32_e32 v147, v99, v99
	v_fma_f32 v132, v132, v191, v190
	v_fma_f32 v133, v133, v191, v190
	v_fma_f32 v134, v134, v191, v190
	v_fma_f32 v135, v135, v191, v190
	v_fma_f32 v136, v136, v191, v190
	v_fma_f32 v137, v137, v191, v190
	v_fma_f32 v138, v138, v191, v190
	v_fma_f32 v139, v139, v191, v190
	v_fma_f32 v140, v140, v191, v190
	v_fma_f32 v141, v141, v191, v190
	v_fma_f32 v142, v142, v191, v190
	v_fma_f32 v143, v143, v191, v190
	v_fma_f32 v144, v144, v191, v190
	v_fma_f32 v145, v145, v191, v190
	v_fma_f32 v146, v146, v191, v190
	v_fma_f32 v147, v147, v191, v190
	v_mul_f32_e32 v132, v132, v80
	v_mul_f32_e32 v133, v133, v81
	v_mul_f32_e32 v134, v134, v82
	v_mul_f32_e32 v135, v135, v83
	v_mul_f32_e32 v136, v136, v84
	v_mul_f32_e32 v137, v137, v85
	v_mul_f32_e32 v138, v138, v86
	v_mul_f32_e32 v139, v139, v87
	v_mul_f32_e32 v140, v140, v92
	v_mul_f32_e32 v141, v141, v93
	v_mul_f32_e32 v142, v142, v94
	v_mul_f32_e32 v143, v143, v95
	v_mul_f32_e32 v144, v144, v96
	v_mul_f32_e32 v145, v145, v97
	v_mul_f32_e32 v146, v146, v98
	v_mul_f32_e32 v147, v147, v99
	v_exp_f32_e32 v132, v132
	v_exp_f32_e32 v133, v133
	v_exp_f32_e32 v134, v134
	v_exp_f32_e32 v135, v135
	v_exp_f32_e32 v136, v136
	v_exp_f32_e32 v137, v137
	v_exp_f32_e32 v138, v138
	v_exp_f32_e32 v139, v139
	v_exp_f32_e32 v140, v140
	v_exp_f32_e32 v141, v141
	v_exp_f32_e32 v142, v142
	v_exp_f32_e32 v143, v143
	v_exp_f32_e32 v144, v144
	v_exp_f32_e32 v145, v145
	v_exp_f32_e32 v146, v146
	v_exp_f32_e32 v147, v147
	s_nop 0
	v_add_f32_e32 v132, 1.0, v132
	v_add_f32_e32 v133, 1.0, v133
	v_add_f32_e32 v134, 1.0, v134
	v_add_f32_e32 v135, 1.0, v135
	v_add_f32_e32 v136, 1.0, v136
	v_add_f32_e32 v137, 1.0, v137
	v_add_f32_e32 v138, 1.0, v138
	v_add_f32_e32 v139, 1.0, v139
	v_add_f32_e32 v140, 1.0, v140
	v_add_f32_e32 v141, 1.0, v141
	v_add_f32_e32 v142, 1.0, v142
	v_add_f32_e32 v143, 1.0, v143
	v_add_f32_e32 v144, 1.0, v144
	v_add_f32_e32 v145, 1.0, v145
	v_add_f32_e32 v146, 1.0, v146
	v_add_f32_e32 v147, 1.0, v147
	v_rcp_f32_e32 v132, v132
	v_rcp_f32_e32 v133, v133
	v_rcp_f32_e32 v134, v134
	v_rcp_f32_e32 v135, v135
	v_rcp_f32_e32 v136, v136
	v_rcp_f32_e32 v137, v137
	v_rcp_f32_e32 v138, v138
	v_rcp_f32_e32 v139, v139
	v_rcp_f32_e32 v140, v140
	v_rcp_f32_e32 v141, v141
	v_rcp_f32_e32 v142, v142
	v_rcp_f32_e32 v143, v143
	v_rcp_f32_e32 v144, v144
	v_rcp_f32_e32 v145, v145
	v_rcp_f32_e32 v146, v146
	v_rcp_f32_e32 v147, v147
	s_nop 0
	v_mul_f32_e32 v80, v80, v132
	v_mul_f32_e32 v81, v81, v133
	v_mul_f32_e32 v82, v82, v134
	v_mul_f32_e32 v83, v83, v135
	v_mul_f32_e32 v84, v84, v136
	v_mul_f32_e32 v85, v85, v137
	v_mul_f32_e32 v86, v86, v138
	v_mul_f32_e32 v87, v87, v139
	v_mul_f32_e32 v92, v92, v140
	v_mul_f32_e32 v93, v93, v141
	v_mul_f32_e32 v94, v94, v142
	v_mul_f32_e32 v95, v95, v143
	v_mul_f32_e32 v96, v96, v144
	v_mul_f32_e32 v97, v97, v145
	v_mul_f32_e32 v98, v98, v146
	v_mul_f32_e32 v99, v99, v147
	v_add_f32_e32 v132, v80, v81
	v_add_f32_e32 v132, v132, v82
	v_add_f32_e32 v132, v132, v83
	v_add_f32_e32 v132, v132, v84
	v_add_f32_e32 v132, v132, v85
	v_add_f32_e32 v132, v132, v86
	v_add_f32_e32 v132, v132, v87
	v_add_f32_e32 v132, v132, v92
	v_add_f32_e32 v132, v132, v93
	v_add_f32_e32 v132, v132, v94
	v_add_f32_e32 v132, v132, v95
	v_add_f32_e32 v132, v132, v96
	v_add_f32_e32 v132, v132, v97
	v_add_f32_e32 v132, v132, v98
	v_add_f32_e32 v132, v132, v99
	s_nop 1
	v_add_f32_dpp v132, v132, v132 quad_perm:[1,0,3,2] row_mask:0xf bank_mask:0xf
	s_nop 1
	v_add_f32_dpp v132, v132, v132 quad_perm:[2,3,0,1] row_mask:0xf bank_mask:0xf
	s_nop 1
	v_add_f32_dpp v132, v132, v132 row_half_mirror row_mask:0xf bank_mask:0xf
	s_nop 1
	v_add_f32_dpp v132, v132, v132 row_mirror row_mask:0xf bank_mask:0xf
	s_nop 1
	v_mul_f32_e32 v132, 0x3b800000, v132
	v_sub_f32_e32 v80, v80, v132
	v_sub_f32_e32 v81, v81, v132
	v_sub_f32_e32 v82, v82, v132
	v_sub_f32_e32 v83, v83, v132
	v_sub_f32_e32 v84, v84, v132
	v_sub_f32_e32 v85, v85, v132
	v_sub_f32_e32 v86, v86, v132
	v_sub_f32_e32 v87, v87, v132
	v_sub_f32_e32 v92, v92, v132
	v_sub_f32_e32 v93, v93, v132
	v_sub_f32_e32 v94, v94, v132
	v_sub_f32_e32 v95, v95, v132
	v_sub_f32_e32 v96, v96, v132
	v_sub_f32_e32 v97, v97, v132
	v_sub_f32_e32 v98, v98, v132
	v_sub_f32_e32 v99, v99, v132
	v_mul_f32_e32 v133, v80, v80
	v_fmac_f32_e32 v133, v81, v81
	v_fmac_f32_e32 v133, v82, v82
	v_fmac_f32_e32 v133, v83, v83
	v_fmac_f32_e32 v133, v84, v84
	v_fmac_f32_e32 v133, v85, v85
	v_fmac_f32_e32 v133, v86, v86
	v_fmac_f32_e32 v133, v87, v87
	v_fmac_f32_e32 v133, v92, v92
	v_fmac_f32_e32 v133, v93, v93
	v_fmac_f32_e32 v133, v94, v94
	v_fmac_f32_e32 v133, v95, v95
	v_fmac_f32_e32 v133, v96, v96
	v_fmac_f32_e32 v133, v97, v97
	v_fmac_f32_e32 v133, v98, v98
	v_fmac_f32_e32 v133, v99, v99
	s_nop 1
	v_add_f32_dpp v133, v133, v133 quad_perm:[1,0,3,2] row_mask:0xf bank_mask:0xf
	s_nop 1
	v_add_f32_dpp v133, v133, v133 quad_perm:[2,3,0,1] row_mask:0xf bank_mask:0xf
	s_nop 1
	v_add_f32_dpp v133, v133, v133 row_half_mirror row_mask:0xf bank_mask:0xf
	s_nop 1
; #define LAS __attribute__((address_space(3)))
; DI unsigned short f2bf(float f) { return (unsigned short)(pk2(f, 0.f) & 0xffffu); }
; DI float gelu_f(float x) { return x * __builtin_amdgcn_rcpf(1.f + __builtin_amdgcn_exp2f(x * (-2.302208198f + -0.102943240f * (x * x)))); }
; __global__ void __launch_bounds__(512, 2) fwd_megakernel(Args args) {
;     ...
;                     float v[64]; float sm = 0.f;
; #pragma unroll
;                     for (int k = 0; k < 8; ++k) { float t8[8]; unpack8(gvr[k], t8);
; #pragma unroll
;                         for (int i = 0; i < 8; ++i) { v[8 * k + i] = gelu_f(t8[i]); sm += v[8 * k + i]; } }
;                     sm += __shfl_xor(sm, 1); sm += __shfl_xor(sm, 2);
;                     const float mean = sm * (1.f / 256.f); float qv = 0.f;
; #pragma unroll
;                     for (int i = 0; i < 64; ++i) { const float d = v[i] - mean; qv += d * d; }
;                     qv += __shfl_xor(qv, 1); qv += __shfl_xor(qv, 2);
;                     const float rstd = rsqrtf(qv * (1.f / 256.f) + EPS);
;                     const float* lw = args.in[16] + layer * 256 + sub * 64; const float* lb = args.in[17] + layer * 256 + sub * 64;
;                     LAS bf16* dst = vnT + sub * (64 * 136) + l;
; #pragma unroll
;                     for (int i = 0; i < 64; ++i) dst[i * 136] = f2bf((v[i] - mean) * rstd * lw[i] + lb[i]);
	v_add_f32_dpp v133, v133, v133 row_mirror row_mask:0xf bank_mask:0xf
	s_nop 1
	v_mov_b32_e32 v134, 0x358637bd
	v_fmamk_f32 v133, v133, 0x3b800000, v134
	v_rsq_f32_e32 v133, v133
	s_nop 0
	v_mul_f32_e32 v80, v80, v133
	v_mul_f32_e32 v81, v81, v133
	v_mul_f32_e32 v82, v82, v133
	v_mul_f32_e32 v83, v83, v133
	v_mul_f32_e32 v84, v84, v133
	v_mul_f32_e32 v85, v85, v133
	v_mul_f32_e32 v86, v86, v133
	v_mul_f32_e32 v87, v87, v133
	v_mul_f32_e32 v92, v92, v133
	v_mul_f32_e32 v93, v93, v133
	v_mul_f32_e32 v94, v94, v133
	v_mul_f32_e32 v95, v95, v133
	v_mul_f32_e32 v96, v96, v133
	v_mul_f32_e32 v97, v97, v133
	v_mul_f32_e32 v98, v98, v133
	v_mul_f32_e32 v99, v99, v133
	v_fma_f32 v80, v80, v32, v48
	v_fma_f32 v81, v81, v33, v49
	v_fma_f32 v82, v82, v34, v50
	v_fma_f32 v83, v83, v35, v51
	v_fma_f32 v84, v84, v36, v52
	v_fma_f32 v85, v85, v37, v53
	v_fma_f32 v86, v86, v38, v54
	v_fma_f32 v87, v87, v39, v55
	v_fma_f32 v92, v92, v40, v56
	v_fma_f32 v93, v93, v41, v57
	v_fma_f32 v94, v94, v42, v58
	v_fma_f32 v95, v95, v43, v59
	v_fma_f32 v96, v96, v44, v60
	v_fma_f32 v97, v97, v45, v61
	v_fma_f32 v98, v98, v46, v62
	v_fma_f32 v99, v99, v47, v63
	v_cvt_pk_bf16_f32 v100, v64, v80
	v_cvt_pk_bf16_f32 v102, v65, v81
	v_cvt_pk_bf16_f32 v104, v66, v82
	v_cvt_pk_bf16_f32 v106, v67, v83
	v_cvt_pk_bf16_f32 v108, v68, v84
	v_cvt_pk_bf16_f32 v110, v69, v85
	v_cvt_pk_bf16_f32 v112, v70, v86
	v_cvt_pk_bf16_f32 v114, v71, v87
	v_cvt_pk_bf16_f32 v116, v72, v92
	v_cvt_pk_bf16_f32 v118, v73, v93
	v_cvt_pk_bf16_f32 v120, v74, v94
	v_cvt_pk_bf16_f32 v122, v75, v95
	v_cvt_pk_bf16_f32 v124, v76, v96
	v_cvt_pk_bf16_f32 v126, v77, v97
	v_cvt_pk_bf16_f32 v128, v78, v98
	v_cvt_pk_bf16_f32 v130, v79, v99
	v_lshlrev_b32_e32 v64, 16, v16
	v_and_b32_e32 v65, 0xffff0000, v16
	v_lshlrev_b32_e32 v66, 16, v17
	v_and_b32_e32 v67, 0xffff0000, v17
	v_lshlrev_b32_e32 v68, 16, v18
	v_and_b32_e32 v69, 0xffff0000, v18
	v_lshlrev_b32_e32 v70, 16, v19
	v_and_b32_e32 v71, 0xffff0000, v19
	v_lshlrev_b32_e32 v72, 16, v20
	v_and_b32_e32 v73, 0xffff0000, v20
	v_lshlrev_b32_e32 v74, 16, v21
	v_and_b32_e32 v75, 0xffff0000, v21
	v_lshlrev_b32_e32 v76, 16, v22
	v_and_b32_e32 v77, 0xffff0000, v22
	v_lshlrev_b32_e32 v78, 16, v23
	v_and_b32_e32 v79, 0xffff0000, v23
	v_mul_f32_e32 v132, v64, v64
	v_mul_f32_e32 v133, v65, v65
	v_mul_f32_e32 v134, v66, v66
	v_mul_f32_e32 v135, v67, v67
	v_mul_f32_e32 v136, v68, v68
	v_mul_f32_e32 v137, v69, v69
	v_mul_f32_e32 v138, v70, v70
	v_mul_f32_e32 v139, v71, v71
	v_mul_f32_e32 v140, v72, v72
	v_mul_f32_e32 v141, v73, v73
	v_mul_f32_e32 v142, v74, v74
	v_mul_f32_e32 v143, v75, v75
	v_mul_f32_e32 v144, v76, v76
	v_mul_f32_e32 v145, v77, v77
	v_mul_f32_e32 v146, v78, v78
	v_mul_f32_e32 v147, v79, v79
	v_fma_f32 v132, v132, v191, v190
	v_fma_f32 v133, v133, v191, v190
	v_fma_f32 v134, v134, v191, v190
	v_fma_f32 v135, v135, v191, v190
	v_fma_f32 v136, v136, v191, v190
	v_fma_f32 v137, v137, v191, v190
	v_fma_f32 v138, v138, v191, v190
	v_fma_f32 v139, v139, v191, v190
	v_fma_f32 v140, v140, v191, v190
	v_fma_f32 v141, v141, v191, v190
	v_fma_f32 v142, v142, v191, v190
	v_fma_f32 v143, v143, v191, v190
	v_fma_f32 v144, v144, v191, v190
	v_fma_f32 v145, v145, v191, v190
	v_fma_f32 v146, v146, v191, v190
	v_fma_f32 v147, v147, v191, v190
	v_mul_f32_e32 v132, v132, v64
	v_mul_f32_e32 v133, v133, v65
	v_mul_f32_e32 v134, v134, v66
	v_mul_f32_e32 v135, v135, v67
	v_mul_f32_e32 v136, v136, v68
	v_mul_f32_e32 v137, v137, v69
	v_mul_f32_e32 v138, v138, v70
	v_mul_f32_e32 v139, v139, v71
	v_mul_f32_e32 v140, v140, v72
	v_mul_f32_e32 v141, v141, v73
	v_mul_f32_e32 v142, v142, v74
	v_mul_f32_e32 v143, v143, v75
	v_mul_f32_e32 v144, v144, v76
	v_mul_f32_e32 v145, v145, v77
	v_mul_f32_e32 v146, v146, v78
	v_mul_f32_e32 v147, v147, v79
	v_exp_f32_e32 v132, v132
	v_exp_f32_e32 v133, v133
	v_exp_f32_e32 v134, v134
	v_exp_f32_e32 v135, v135
	v_exp_f32_e32 v136, v136
	v_exp_f32_e32 v137, v137
	v_exp_f32_e32 v138, v138
	v_exp_f32_e32 v139, v139
	v_exp_f32_e32 v140, v140
	v_exp_f32_e32 v141, v141
	v_exp_f32_e32 v142, v142
	v_exp_f32_e32 v143, v143
	v_exp_f32_e32 v144, v144
	v_exp_f32_e32 v145, v145
	v_exp_f32_e32 v146, v146
	v_exp_f32_e32 v147, v147
	s_nop 0
	v_add_f32_e32 v132, 1.0, v132
	v_add_f32_e32 v133, 1.0, v133
	v_add_f32_e32 v134, 1.0, v134
	v_add_f32_e32 v135, 1.0, v135
	v_add_f32_e32 v136, 1.0, v136
	v_add_f32_e32 v137, 1.0, v137
	v_add_f32_e32 v138, 1.0, v138
	v_add_f32_e32 v139, 1.0, v139
	v_add_f32_e32 v140, 1.0, v140
	v_add_f32_e32 v141, 1.0, v141
	v_add_f32_e32 v142, 1.0, v142
	v_add_f32_e32 v143, 1.0, v143
	v_add_f32_e32 v144, 1.0, v144
	v_add_f32_e32 v145, 1.0, v145
	v_add_f32_e32 v146, 1.0, v146
	v_add_f32_e32 v147, 1.0, v147
	v_rcp_f32_e32 v132, v132
	v_rcp_f32_e32 v133, v133
	v_rcp_f32_e32 v134, v134
	v_rcp_f32_e32 v135, v135
	v_rcp_f32_e32 v136, v136
	v_rcp_f32_e32 v137, v137
	v_rcp_f32_e32 v138, v138
	v_rcp_f32_e32 v139, v139
	v_rcp_f32_e32 v140, v140
	v_rcp_f32_e32 v141, v141
	v_rcp_f32_e32 v142, v142
	v_rcp_f32_e32 v143, v143
	v_rcp_f32_e32 v144, v144
	v_rcp_f32_e32 v145, v145
	v_rcp_f32_e32 v146, v146
	v_rcp_f32_e32 v147, v147
	s_nop 0
	v_mul_f32_e32 v64, v64, v132
	v_mul_f32_e32 v65, v65, v133
	v_mul_f32_e32 v66, v66, v134
	v_mul_f32_e32 v67, v67, v135
	v_mul_f32_e32 v68, v68, v136
	v_mul_f32_e32 v69, v69, v137
	v_mul_f32_e32 v70, v70, v138
	v_mul_f32_e32 v71, v71, v139
	v_mul_f32_e32 v72, v72, v140
	v_mul_f32_e32 v73, v73, v141
	v_mul_f32_e32 v74, v74, v142
	v_mul_f32_e32 v75, v75, v143
	v_mul_f32_e32 v76, v76, v144
	v_mul_f32_e32 v77, v77, v145
	v_mul_f32_e32 v78, v78, v146
	v_mul_f32_e32 v79, v79, v147
	v_add_f32_e32 v132, v64, v65
	v_add_f32_e32 v132, v132, v66
; #define LAS __attribute__((address_space(3)))
; DI unsigned short f2bf(float f) { return (unsigned short)(pk2(f, 0.f) & 0xffffu); }
; DI float gelu_f(float x) { return x * __builtin_amdgcn_rcpf(1.f + __builtin_amdgcn_exp2f(x * (-2.302208198f + -0.102943240f * (x * x)))); }
; __global__ void __launch_bounds__(512, 2) fwd_megakernel(Args args) {
;     ...
;                     float v[64]; float sm = 0.f;
; #pragma unroll
;                     for (int k = 0; k < 8; ++k) { float t8[8]; unpack8(gvr[k], t8);
; #pragma unroll
;                         for (int i = 0; i < 8; ++i) { v[8 * k + i] = gelu_f(t8[i]); sm += v[8 * k + i]; } }
;                     sm += __shfl_xor(sm, 1); sm += __shfl_xor(sm, 2);
;                     const float mean = sm * (1.f / 256.f); float qv = 0.f;
; #pragma unroll
;                     for (int i = 0; i < 64; ++i) { const float d = v[i] - mean; qv += d * d; }
;                     qv += __shfl_xor(qv, 1); qv += __shfl_xor(qv, 2);
;                     const float rstd = rsqrtf(qv * (1.f / 256.f) + EPS);
;                     const float* lw = args.in[16] + layer * 256 + sub * 64; const float* lb = args.in[17] + layer * 256 + sub * 64;
;                     LAS bf16* dst = vnT + sub * (64 * 136) + l;
; #pragma unroll
;                     for (int i = 0; i < 64; ++i) dst[i * 136] = f2bf((v[i] - mean) * rstd * lw[i] + lb[i]);
	v_add_f32_e32 v132, v132, v67
	v_add_f32_e32 v132, v132, v68
	v_add_f32_e32 v132, v132, v69
	v_add_f32_e32 v132, v132, v70
	v_add_f32_e32 v132, v132, v71
	v_add_f32_e32 v132, v132, v72
	v_add_f32_e32 v132, v132, v73
	v_add_f32_e32 v132, v132, v74
	v_add_f32_e32 v132, v132, v75
	v_add_f32_e32 v132, v132, v76
	v_add_f32_e32 v132, v132, v77
	v_add_f32_e32 v132, v132, v78
	v_add_f32_e32 v132, v132, v79
	s_nop 1
	v_add_f32_dpp v132, v132, v132 quad_perm:[1,0,3,2] row_mask:0xf bank_mask:0xf
	s_nop 1
	v_add_f32_dpp v132, v132, v132 quad_perm:[2,3,0,1] row_mask:0xf bank_mask:0xf
	s_nop 1
	v_add_f32_dpp v132, v132, v132 row_half_mirror row_mask:0xf bank_mask:0xf
	s_nop 1
	v_add_f32_dpp v132, v132, v132 row_mirror row_mask:0xf bank_mask:0xf
	s_nop 1
	v_mul_f32_e32 v132, 0x3b800000, v132
	v_sub_f32_e32 v64, v64, v132
	v_sub_f32_e32 v65, v65, v132
	v_sub_f32_e32 v66, v66, v132
	v_sub_f32_e32 v67, v67, v132
	v_sub_f32_e32 v68, v68, v132
	v_sub_f32_e32 v69, v69, v132
	v_sub_f32_e32 v70, v70, v132
	v_sub_f32_e32 v71, v71, v132
	v_sub_f32_e32 v72, v72, v132
	v_sub_f32_e32 v73, v73, v132
	v_sub_f32_e32 v74, v74, v132
	v_sub_f32_e32 v75, v75, v132
	v_sub_f32_e32 v76, v76, v132
	v_sub_f32_e32 v77, v77, v132
	v_sub_f32_e32 v78, v78, v132
	v_sub_f32_e32 v79, v79, v132
	v_mul_f32_e32 v133, v64, v64
	v_fmac_f32_e32 v133, v65, v65
	v_fmac_f32_e32 v133, v66, v66
	v_fmac_f32_e32 v133, v67, v67
	v_fmac_f32_e32 v133, v68, v68
	v_fmac_f32_e32 v133, v69, v69
	v_fmac_f32_e32 v133, v70, v70
	v_fmac_f32_e32 v133, v71, v71
	v_fmac_f32_e32 v133, v72, v72
	v_fmac_f32_e32 v133, v73, v73
	v_fmac_f32_e32 v133, v74, v74
	v_fmac_f32_e32 v133, v75, v75
	v_fmac_f32_e32 v133, v76, v76
	v_fmac_f32_e32 v133, v77, v77
	v_fmac_f32_e32 v133, v78, v78
	v_fmac_f32_e32 v133, v79, v79
	s_nop 1
	v_add_f32_dpp v133, v133, v133 quad_perm:[1,0,3,2] row_mask:0xf bank_mask:0xf
	s_nop 1
	v_add_f32_dpp v133, v133, v133 quad_perm:[2,3,0,1] row_mask:0xf bank_mask:0xf
	s_nop 1
	v_add_f32_dpp v133, v133, v133 row_half_mirror row_mask:0xf bank_mask:0xf
	s_nop 1
	v_add_f32_dpp v133, v133, v133 row_mirror row_mask:0xf bank_mask:0xf
	s_nop 1
	v_mov_b32_e32 v134, 0x358637bd
	v_fmamk_f32 v133, v133, 0x3b800000, v134
	v_rsq_f32_e32 v133, v133
	s_nop 0
	v_mul_f32_e32 v64, v64, v133
	v_mul_f32_e32 v65, v65, v133
	v_mul_f32_e32 v66, v66, v133
	v_mul_f32_e32 v67, v67, v133
	v_mul_f32_e32 v68, v68, v133
	v_mul_f32_e32 v69, v69, v133
	v_mul_f32_e32 v70, v70, v133
	v_mul_f32_e32 v71, v71, v133
	v_mul_f32_e32 v72, v72, v133
	v_mul_f32_e32 v73, v73, v133
	v_mul_f32_e32 v74, v74, v133
	v_mul_f32_e32 v75, v75, v133
	v_mul_f32_e32 v76, v76, v133
	v_mul_f32_e32 v77, v77, v133
	v_mul_f32_e32 v78, v78, v133
	v_mul_f32_e32 v79, v79, v133
	v_fma_f32 v64, v64, v32, v48
	v_fma_f32 v65, v65, v33, v49
	v_fma_f32 v66, v66, v34, v50
	v_fma_f32 v67, v67, v35, v51
	v_fma_f32 v68, v68, v36, v52
	v_fma_f32 v69, v69, v37, v53
	v_fma_f32 v70, v70, v38, v54
	v_fma_f32 v71, v71, v39, v55
	v_fma_f32 v72, v72, v40, v56
	v_fma_f32 v73, v73, v41, v57
	v_fma_f32 v74, v74, v42, v58
	v_fma_f32 v75, v75, v43, v59
	v_fma_f32 v76, v76, v44, v60
	v_fma_f32 v77, v77, v45, v61
	v_fma_f32 v78, v78, v46, v62
	v_fma_f32 v79, v79, v47, v63
	v_lshlrev_b32_e32 v80, 16, v24
	v_and_b32_e32 v81, 0xffff0000, v24
	v_lshlrev_b32_e32 v82, 16, v25
	v_and_b32_e32 v83, 0xffff0000, v25
	v_lshlrev_b32_e32 v84, 16, v26
	v_and_b32_e32 v85, 0xffff0000, v26
	v_lshlrev_b32_e32 v86, 16, v27
	v_and_b32_e32 v87, 0xffff0000, v27
	v_lshlrev_b32_e32 v92, 16, v28
	v_and_b32_e32 v93, 0xffff0000, v28
	v_lshlrev_b32_e32 v94, 16, v29
	v_and_b32_e32 v95, 0xffff0000, v29
	v_lshlrev_b32_e32 v96, 16, v30
	v_and_b32_e32 v97, 0xffff0000, v30
	v_lshlrev_b32_e32 v98, 16, v31
	v_and_b32_e32 v99, 0xffff0000, v31
	v_mul_f32_e32 v132, v80, v80
	v_mul_f32_e32 v133, v81, v81
	v_mul_f32_e32 v134, v82, v82
	v_mul_f32_e32 v135, v83, v83
	v_mul_f32_e32 v136, v84, v84
	v_mul_f32_e32 v137, v85, v85
	v_mul_f32_e32 v138, v86, v86
	v_mul_f32_e32 v139, v87, v87
	v_mul_f32_e32 v140, v92, v92
	v_mul_f32_e32 v141, v93, v93
	v_mul_f32_e32 v142, v94, v94
	v_mul_f32_e32 v143, v95, v95
	v_mul_f32_e32 v144, v96, v96
	v_mul_f32_e32 v145, v97, v97
	v_mul_f32_e32 v146, v98, v98
	v_mul_f32_e32 v147, v99, v99
	v_fma_f32 v132, v132, v191, v190
	v_fma_f32 v133, v133, v191, v190
	v_fma_f32 v134, v134, v191, v190
	v_fma_f32 v135, v135, v191, v190
	v_fma_f32 v136, v136, v191, v190
	v_fma_f32 v137, v137, v191, v190
	v_fma_f32 v138, v138, v191, v190
	v_fma_f32 v139, v139, v191, v190
	v_fma_f32 v140, v140, v191, v190
	v_fma_f32 v141, v141, v191, v190
	v_fma_f32 v142, v142, v191, v190
	v_fma_f32 v143, v143, v191, v190
	v_fma_f32 v144, v144, v191, v190
	v_fma_f32 v145, v145, v191, v190
	v_fma_f32 v146, v146, v191, v190
	v_fma_f32 v147, v147, v191, v190
	v_mul_f32_e32 v132, v132, v80
	v_mul_f32_e32 v133, v133, v81
	v_mul_f32_e32 v134, v134, v82
	v_mul_f32_e32 v135, v135, v83
	v_mul_f32_e32 v136, v136, v84
	v_mul_f32_e32 v137, v137, v85
	v_mul_f32_e32 v138, v138, v86
	v_mul_f32_e32 v139, v139, v87
	v_mul_f32_e32 v140, v140, v92
	v_mul_f32_e32 v141, v141, v93
	v_mul_f32_e32 v142, v142, v94
	v_mul_f32_e32 v143, v143, v95
	v_mul_f32_e32 v144, v144, v96
	v_mul_f32_e32 v145, v145, v97
	v_mul_f32_e32 v146, v146, v98
	v_mul_f32_e32 v147, v147, v99
	v_exp_f32_e32 v132, v132
	v_exp_f32_e32 v133, v133
	v_exp_f32_e32 v134, v134
	v_exp_f32_e32 v135, v135
	v_exp_f32_e32 v136, v136
	v_exp_f32_e32 v137, v137
	v_exp_f32_e32 v138, v138
	v_exp_f32_e32 v139, v139
	v_exp_f32_e32 v140, v140
	v_exp_f32_e32 v141, v141
	v_exp_f32_e32 v142, v142
	v_exp_f32_e32 v143, v143
	v_exp_f32_e32 v144, v144
	v_exp_f32_e32 v145, v145
	v_exp_f32_e32 v146, v146
; #define LAS __attribute__((address_space(3)))
; DI unsigned short f2bf(float f) { return (unsigned short)(pk2(f, 0.f) & 0xffffu); }
; DI float gelu_f(float x) { return x * __builtin_amdgcn_rcpf(1.f + __builtin_amdgcn_exp2f(x * (-2.302208198f + -0.102943240f * (x * x)))); }
; __global__ void __launch_bounds__(512, 2) fwd_megakernel(Args args) {
;     ...
;                     float v[64]; float sm = 0.f;
; #pragma unroll
;                     for (int k = 0; k < 8; ++k) { float t8[8]; unpack8(gvr[k], t8);
; #pragma unroll
;                         for (int i = 0; i < 8; ++i) { v[8 * k + i] = gelu_f(t8[i]); sm += v[8 * k + i]; } }
;                     sm += __shfl_xor(sm, 1); sm += __shfl_xor(sm, 2);
;                     const float mean = sm * (1.f / 256.f); float qv = 0.f;
; #pragma unroll
;                     for (int i = 0; i < 64; ++i) { const float d = v[i] - mean; qv += d * d; }
;                     qv += __shfl_xor(qv, 1); qv += __shfl_xor(qv, 2);
;                     const float rstd = rsqrtf(qv * (1.f / 256.f) + EPS);
;                     const float* lw = args.in[16] + layer * 256 + sub * 64; const float* lb = args.in[17] + layer * 256 + sub * 64;
;                     LAS bf16* dst = vnT + sub * (64 * 136) + l;
; #pragma unroll
;                     for (int i = 0; i < 64; ++i) dst[i * 136] = f2bf((v[i] - mean) * rstd * lw[i] + lb[i]);
	v_exp_f32_e32 v147, v147
	s_nop 0
	v_add_f32_e32 v132, 1.0, v132
	v_add_f32_e32 v133, 1.0, v133
	v_add_f32_e32 v134, 1.0, v134
	v_add_f32_e32 v135, 1.0, v135
	v_add_f32_e32 v136, 1.0, v136
	v_add_f32_e32 v137, 1.0, v137
	v_add_f32_e32 v138, 1.0, v138
	v_add_f32_e32 v139, 1.0, v139
	v_add_f32_e32 v140, 1.0, v140
	v_add_f32_e32 v141, 1.0, v141
	v_add_f32_e32 v142, 1.0, v142
	v_add_f32_e32 v143, 1.0, v143
	v_add_f32_e32 v144, 1.0, v144
	v_add_f32_e32 v145, 1.0, v145
	v_add_f32_e32 v146, 1.0, v146
	v_add_f32_e32 v147, 1.0, v147
	v_rcp_f32_e32 v132, v132
	v_rcp_f32_e32 v133, v133
	v_rcp_f32_e32 v134, v134
	v_rcp_f32_e32 v135, v135
	v_rcp_f32_e32 v136, v136
	v_rcp_f32_e32 v137, v137
	v_rcp_f32_e32 v138, v138
	v_rcp_f32_e32 v139, v139
	v_rcp_f32_e32 v140, v140
	v_rcp_f32_e32 v141, v141
	v_rcp_f32_e32 v142, v142
	v_rcp_f32_e32 v143, v143
	v_rcp_f32_e32 v144, v144
	v_rcp_f32_e32 v145, v145
	v_rcp_f32_e32 v146, v146
	v_rcp_f32_e32 v147, v147
	s_nop 0
	v_mul_f32_e32 v80, v80, v132
	v_mul_f32_e32 v81, v81, v133
	v_mul_f32_e32 v82, v82, v134
	v_mul_f32_e32 v83, v83, v135
	v_mul_f32_e32 v84, v84, v136
	v_mul_f32_e32 v85, v85, v137
	v_mul_f32_e32 v86, v86, v138
	v_mul_f32_e32 v87, v87, v139
	v_mul_f32_e32 v92, v92, v140
	v_mul_f32_e32 v93, v93, v141
	v_mul_f32_e32 v94, v94, v142
	v_mul_f32_e32 v95, v95, v143
	v_mul_f32_e32 v96, v96, v144
	v_mul_f32_e32 v97, v97, v145
	v_mul_f32_e32 v98, v98, v146
	v_mul_f32_e32 v99, v99, v147
	v_add_f32_e32 v132, v80, v81
	v_add_f32_e32 v132, v132, v82
	v_add_f32_e32 v132, v132, v83
	v_add_f32_e32 v132, v132, v84
	v_add_f32_e32 v132, v132, v85
	v_add_f32_e32 v132, v132, v86
	v_add_f32_e32 v132, v132, v87
	v_add_f32_e32 v132, v132, v92
	v_add_f32_e32 v132, v132, v93
	v_add_f32_e32 v132, v132, v94
	v_add_f32_e32 v132, v132, v95
	v_add_f32_e32 v132, v132, v96
	v_add_f32_e32 v132, v132, v97
	v_add_f32_e32 v132, v132, v98
	v_add_f32_e32 v132, v132, v99
	s_nop 1
	v_add_f32_dpp v132, v132, v132 quad_perm:[1,0,3,2] row_mask:0xf bank_mask:0xf
	s_nop 1
	v_add_f32_dpp v132, v132, v132 quad_perm:[2,3,0,1] row_mask:0xf bank_mask:0xf
	s_nop 1
	v_add_f32_dpp v132, v132, v132 row_half_mirror row_mask:0xf bank_mask:0xf
	s_nop 1
	v_add_f32_dpp v132, v132, v132 row_mirror row_mask:0xf bank_mask:0xf
	s_nop 1
	v_mul_f32_e32 v132, 0x3b800000, v132
	v_sub_f32_e32 v80, v80, v132
	v_sub_f32_e32 v81, v81, v132
	v_sub_f32_e32 v82, v82, v132
	v_sub_f32_e32 v83, v83, v132
	v_sub_f32_e32 v84, v84, v132
	v_sub_f32_e32 v85, v85, v132
	v_sub_f32_e32 v86, v86, v132
	v_sub_f32_e32 v87, v87, v132
	v_sub_f32_e32 v92, v92, v132
	v_sub_f32_e32 v93, v93, v132
	v_sub_f32_e32 v94, v94, v132
	v_sub_f32_e32 v95, v95, v132
	v_sub_f32_e32 v96, v96, v132
	v_sub_f32_e32 v97, v97, v132
	v_sub_f32_e32 v98, v98, v132
	v_sub_f32_e32 v99, v99, v132
	v_mul_f32_e32 v133, v80, v80
	v_fmac_f32_e32 v133, v81, v81
	v_fmac_f32_e32 v133, v82, v82
	v_fmac_f32_e32 v133, v83, v83
	v_fmac_f32_e32 v133, v84, v84
	v_fmac_f32_e32 v133, v85, v85
	v_fmac_f32_e32 v133, v86, v86
	v_fmac_f32_e32 v133, v87, v87
	v_fmac_f32_e32 v133, v92, v92
	v_fmac_f32_e32 v133, v93, v93
	v_fmac_f32_e32 v133, v94, v94
	v_fmac_f32_e32 v133, v95, v95
	v_fmac_f32_e32 v133, v96, v96
	v_fmac_f32_e32 v133, v97, v97
	v_fmac_f32_e32 v133, v98, v98
	v_fmac_f32_e32 v133, v99, v99
	s_nop 1
	v_add_f32_dpp v133, v133, v133 quad_perm:[1,0,3,2] row_mask:0xf bank_mask:0xf
	s_nop 1
	v_add_f32_dpp v133, v133, v133 quad_perm:[2,3,0,1] row_mask:0xf bank_mask:0xf
	s_nop 1
	v_add_f32_dpp v133, v133, v133 row_half_mirror row_mask:0xf bank_mask:0xf
	s_nop 1
	v_add_f32_dpp v133, v133, v133 row_mirror row_mask:0xf bank_mask:0xf
	s_nop 1
	v_mov_b32_e32 v134, 0x358637bd
	v_fmamk_f32 v133, v133, 0x3b800000, v134
	v_rsq_f32_e32 v133, v133
	s_nop 0
	v_mul_f32_e32 v80, v80, v133
	v_mul_f32_e32 v81, v81, v133
	v_mul_f32_e32 v82, v82, v133
	v_mul_f32_e32 v83, v83, v133
	v_mul_f32_e32 v84, v84, v133
	v_mul_f32_e32 v85, v85, v133
	v_mul_f32_e32 v86, v86, v133
	v_mul_f32_e32 v87, v87, v133
	v_mul_f32_e32 v92, v92, v133
	v_mul_f32_e32 v93, v93, v133
	v_mul_f32_e32 v94, v94, v133
	v_mul_f32_e32 v95, v95, v133
	v_mul_f32_e32 v96, v96, v133
	v_mul_f32_e32 v97, v97, v133
	v_mul_f32_e32 v98, v98, v133
	v_mul_f32_e32 v99, v99, v133
	v_fma_f32 v80, v80, v32, v48
	v_fma_f32 v81, v81, v33, v49
	v_fma_f32 v82, v82, v34, v50
	v_fma_f32 v83, v83, v35, v51
	v_fma_f32 v84, v84, v36, v52
	v_fma_f32 v85, v85, v37, v53
	v_fma_f32 v86, v86, v38, v54
	v_fma_f32 v87, v87, v39, v55
	v_fma_f32 v92, v92, v40, v56
	v_fma_f32 v93, v93, v41, v57
	v_fma_f32 v94, v94, v42, v58
	v_fma_f32 v95, v95, v43, v59
	v_fma_f32 v96, v96, v44, v60
	v_fma_f32 v97, v97, v45, v61
	v_fma_f32 v98, v98, v46, v62
	v_fma_f32 v99, v99, v47, v63
	v_cvt_pk_bf16_f32 v101, v64, v80
	v_cvt_pk_bf16_f32 v103, v65, v81
	v_cvt_pk_bf16_f32 v105, v66, v82
	v_cvt_pk_bf16_f32 v107, v67, v83
	v_cvt_pk_bf16_f32 v109, v68, v84
	v_cvt_pk_bf16_f32 v111, v69, v85
	v_cvt_pk_bf16_f32 v113, v70, v86
	v_cvt_pk_bf16_f32 v115, v71, v87
	v_cvt_pk_bf16_f32 v117, v72, v92
	v_cvt_pk_bf16_f32 v119, v73, v93
	v_cvt_pk_bf16_f32 v121, v74, v94
	v_cvt_pk_bf16_f32 v123, v75, v95
	v_cvt_pk_bf16_f32 v125, v76, v96
	v_cvt_pk_bf16_f32 v127, v77, v97
	v_cvt_pk_bf16_f32 v129, v78, v98
	v_cvt_pk_bf16_f32 v131, v79, v99
	ds_write_b64 v189, v[100:101] offset:0
	ds_write_b64 v189, v[102:103] offset:272
	ds_write_b64 v189, v[104:105] offset:544
	ds_write_b64 v189, v[106:107] offset:816
	ds_write_b64 v189, v[108:109] offset:1088
	ds_write_b64 v189, v[110:111] offset:1360
	ds_write_b64 v189, v[112:113] offset:1632
	ds_write_b64 v189, v[114:115] offset:1904
	ds_write_b64 v189, v[116:117] offset:2176
	ds_write_b64 v189, v[118:119] offset:2448
	ds_write_b64 v189, v[120:121] offset:2720
	ds_write_b64 v189, v[122:123] offset:2992
	ds_write_b64 v189, v[124:125] offset:3264
	ds_write_b64 v189, v[126:127] offset:3536
	ds_write_b64 v189, v[128:129] offset:3808
	ds_write_b64 v189, v[130:131] offset:4080
	s_waitcnt lgkmcnt(0)
; DI f32x4 mfma16(bf16x8 a, bf16x8 b, f32x4 c) { return __builtin_amdgcn_mfma_f32_16x16x32_bf16(a, b, c, 0, 0, 0); }
; __global__ void __launch_bounds__(512, 2) fwd_megakernel(Args args) {
;     ...
;                 for (int gi = 0; gi < 4; ++gi)
; #pragma unroll
;                     for (int ks = 0; ks < 4; ++ks) wa[gi][ks] = *(const bf16x8*)(sguW + (size_t)(layer * 4 + gi) * 16384 + (16 * wave + r16) * 128 + ks * 32 + q4 * 8);
;                 __syncthreads();
;                 {
;                     f32x4 og[4][4]; float ss[4] = {0.f, 0.f, 0.f, 0.f};
; #pragma unroll
;                     for (int gi = 0; gi < 4; ++gi) {
;                         f32x4 acc[4];
; #pragma unroll
;                         for (int dt = 0; dt < 4; ++dt) acc[dt] = (f32x4){0.f, 0.f, 0.f, 0.f};
; #pragma unroll
;                         for (int ks = 0; ks < 4; ++ks) {
;                             if (2 * ks <= wave) {
; #pragma unroll
;                                 for (int dt = 0; dt < 4; ++dt) acc[dt] = mfma16(wa[gi][ks], lds_frag(vnT + gi * (64 * 136), 16 * dt + r16, 136, ks * 32 + q4 * 8), acc[dt]);
;                             }
;                         }
	v_lshlrev_b32_e32 v188, 8, v187
	v_lshl_add_u32 v188, v186, 4, v188
	global_load_dwordx4 v[64:67], v188, s[12:13] offset:0
	global_load_dwordx4 v[68:71], v188, s[12:13] offset:64
	global_load_dwordx4 v[72:75], v188, s[12:13] offset:128
	global_load_dwordx4 v[76:79], v188, s[12:13] offset:192
	v_add_u32_e32 v188, 0x8000, v188
	global_load_dwordx4 v[80:83], v188, s[12:13] offset:0
	global_load_dwordx4 v[84:87], v188, s[12:13] offset:64
	global_load_dwordx4 v[92:95], v188, s[12:13] offset:128
	global_load_dwordx4 v[96:99], v188, s[12:13] offset:192
	v_add_u32_e32 v188, 0x8000, v188
	global_load_dwordx4 v[100:103], v188, s[12:13] offset:0
	global_load_dwordx4 v[104:107], v188, s[12:13] offset:64
	global_load_dwordx4 v[108:111], v188, s[12:13] offset:128
	global_load_dwordx4 v[112:115], v188, s[12:13] offset:192
	v_add_u32_e32 v188, 0x8000, v188
	global_load_dwordx4 v[116:119], v188, s[12:13] offset:0
	global_load_dwordx4 v[120:123], v188, s[12:13] offset:64
	global_load_dwordx4 v[124:127], v188, s[12:13] offset:128
	global_load_dwordx4 v[128:131], v188, s[12:13] offset:192
	v_mul_u32_u24_e32 v197, 0x110, v185
	v_lshl_add_u32 v197, v186, 4, v197
	s_waitcnt lgkmcnt(0)
	s_barrier
	s_waitcnt vmcnt(0)
	ds_read_b128 v[132:135], v197 offset:0
	ds_read_b128 v[136:139], v197 offset:4352
	ds_read_b128 v[140:143], v197 offset:8704
	ds_read_b128 v[144:147], v197 offset:13056
	s_waitcnt lgkmcnt(0)
	v_mfma_f32_16x16x32_bf16 v[0:3], v[132:135], v[64:67], 0
	v_mfma_f32_16x16x32_bf16 v[4:7], v[136:139], v[64:67], 0
	v_mfma_f32_16x16x32_bf16 v[8:11], v[140:143], v[64:67], 0
	v_mfma_f32_16x16x32_bf16 v[12:15], v[144:147], v[64:67], 0
	s_cmp_lt_u32 s2, 2
	s_cbranch_scc1 .Lm1c_g0_done
	ds_read_b128 v[132:135], v197 offset:64
	ds_read_b128 v[136:139], v197 offset:4416
	ds_read_b128 v[140:143], v197 offset:8768
	ds_read_b128 v[144:147], v197 offset:13120
	s_waitcnt lgkmcnt(0)
	v_mfma_f32_16x16x32_bf16 v[0:3], v[132:135], v[68:71], v[0:3]
	v_mfma_f32_16x16x32_bf16 v[4:7], v[136:139], v[68:71], v[4:7]
	v_mfma_f32_16x16x32_bf16 v[8:11], v[140:143], v[68:71], v[8:11]
	v_mfma_f32_16x16x32_bf16 v[12:15], v[144:147], v[68:71], v[12:15]
	s_cmp_lt_u32 s2, 4
	s_cbranch_scc1 .Lm1c_g0_done
	ds_read_b128 v[132:135], v197 offset:128
	ds_read_b128 v[136:139], v197 offset:4480
	ds_read_b128 v[140:143], v197 offset:8832
	ds_read_b128 v[144:147], v197 offset:13184
	s_waitcnt lgkmcnt(0)
	v_mfma_f32_16x16x32_bf16 v[0:3], v[132:135], v[72:75], v[0:3]
	v_mfma_f32_16x16x32_bf16 v[4:7], v[136:139], v[72:75], v[4:7]
	v_mfma_f32_16x16x32_bf16 v[8:11], v[140:143], v[72:75], v[8:11]
	v_mfma_f32_16x16x32_bf16 v[12:15], v[144:147], v[72:75], v[12:15]
	s_cmp_lt_u32 s2, 6
	s_cbranch_scc1 .Lm1c_g0_done
	ds_read_b128 v[132:135], v197 offset:192
	ds_read_b128 v[136:139], v197 offset:4544
	ds_read_b128 v[140:143], v197 offset:8896
	ds_read_b128 v[144:147], v197 offset:13248
	s_waitcnt lgkmcnt(0)
	v_mfma_f32_16x16x32_bf16 v[0:3], v[132:135], v[76:79], v[0:3]
	v_mfma_f32_16x16x32_bf16 v[4:7], v[136:139], v[76:79], v[4:7]
	v_mfma_f32_16x16x32_bf16 v[8:11], v[140:143], v[76:79], v[8:11]
	v_mfma_f32_16x16x32_bf16 v[12:15], v[144:147], v[76:79], v[12:15]
.Lm1c_g0_done:
	ds_read_b128 v[132:135], v197 offset:17408
	ds_read_b128 v[136:139], v197 offset:21760
	ds_read_b128 v[140:143], v197 offset:26112
	ds_read_b128 v[144:147], v197 offset:30464
	s_waitcnt lgkmcnt(0)
	v_mfma_f32_16x16x32_bf16 v[16:19], v[132:135], v[80:83], 0
	v_mfma_f32_16x16x32_bf16 v[20:23], v[136:139], v[80:83], 0
	v_mfma_f32_16x16x32_bf16 v[24:27], v[140:143], v[80:83], 0
	v_mfma_f32_16x16x32_bf16 v[28:31], v[144:147], v[80:83], 0
	s_cmp_lt_u32 s2, 2
	s_cbranch_scc1 .Lm1c_g1_done
	ds_read_b128 v[132:135], v197 offset:17472
	ds_read_b128 v[136:139], v197 offset:21824
	ds_read_b128 v[140:143], v197 offset:26176
	ds_read_b128 v[144:147], v197 offset:30528
	s_waitcnt lgkmcnt(0)
	v_mfma_f32_16x16x32_bf16 v[16:19], v[132:135], v[84:87], v[16:19]
	v_mfma_f32_16x16x32_bf16 v[20:23], v[136:139], v[84:87], v[20:23]
	v_mfma_f32_16x16x32_bf16 v[24:27], v[140:143], v[84:87], v[24:27]
	v_mfma_f32_16x16x32_bf16 v[28:31], v[144:147], v[84:87], v[28:31]
	s_cmp_lt_u32 s2, 4
	s_cbranch_scc1 .Lm1c_g1_done
	ds_read_b128 v[132:135], v197 offset:17536
	ds_read_b128 v[136:139], v197 offset:21888
	ds_read_b128 v[140:143], v197 offset:26240
	ds_read_b128 v[144:147], v197 offset:30592
	s_waitcnt lgkmcnt(0)
	v_mfma_f32_16x16x32_bf16 v[16:19], v[132:135], v[92:95], v[16:19]
	v_mfma_f32_16x16x32_bf16 v[20:23], v[136:139], v[92:95], v[20:23]
	v_mfma_f32_16x16x32_bf16 v[24:27], v[140:143], v[92:95], v[24:27]
	v_mfma_f32_16x16x32_bf16 v[28:31], v[144:147], v[92:95], v[28:31]
	s_cmp_lt_u32 s2, 6
	s_cbranch_scc1 .Lm1c_g1_done
	ds_read_b128 v[132:135], v197 offset:17600
	ds_read_b128 v[136:139], v197 offset:21952
	ds_read_b128 v[140:143], v197 offset:26304
	ds_read_b128 v[144:147], v197 offset:30656
	s_waitcnt lgkmcnt(0)
	v_mfma_f32_16x16x32_bf16 v[16:19], v[132:135], v[96:99], v[16:19]
	v_mfma_f32_16x16x32_bf16 v[20:23], v[136:139], v[96:99], v[20:23]
	v_mfma_f32_16x16x32_bf16 v[24:27], v[140:143], v[96:99], v[24:27]
	v_mfma_f32_16x16x32_bf16 v[28:31], v[144:147], v[96:99], v[28:31]
; DI float bf2f(unsigned short b) { return __uint_as_float((unsigned)b << 16); }
; DI float gelu_f(float x) { return x * __builtin_amdgcn_rcpf(1.f + __builtin_amdgcn_exp2f(x * (-2.302208198f + -0.102943240f * (x * x)))); }
; DI f32x4 mfma16(bf16x8 a, bf16x8 b, f32x4 c) { return __builtin_amdgcn_mfma_f32_16x16x32_bf16(a, b, c, 0, 0, 0); }
; __global__ void __launch_bounds__(512, 2) fwd_megakernel(Args args) {
;     ...
;                     for (int gi = 0; gi < 4; ++gi) {
;                         f32x4 acc[4];
; #pragma unroll
;                         for (int dt = 0; dt < 4; ++dt) acc[dt] = (f32x4){0.f, 0.f, 0.f, 0.f};
; #pragma unroll
;                         for (int ks = 0; ks < 4; ++ks) {
;                             if (2 * ks <= wave) {
; #pragma unroll
;                                 for (int dt = 0; dt < 4; ++dt) acc[dt] = mfma16(wa[gi][ks], lds_frag(vnT + gi * (64 * 136), 16 * dt + r16, 136, ks * 32 + q4 * 8), acc[dt]);
;                             }
;                         }
; #pragma unroll
;                         for (int j = 0; j < 4; ++j) {
;                             const int t = 16 * wave + q4 * 4 + j; const float bs = args.in[19][(layer * 4 + gi) * 128 + t];
; #pragma unroll
;                             for (int dt = 0; dt < 4; ++dt) {
;                                 const float uu = gelu_f(bf2f(Us[t * 264 + gi * 64 + 16 * dt + r16]));
;                                 const float o = uu * (acc[dt][j] + bs); ss[j] += o * o; og[gi][dt][j] = o;
;                             }
;                         }
.Lm1c_g1_done:
	ds_read_b128 v[132:135], v197 offset:34816
	ds_read_b128 v[136:139], v197 offset:39168
	ds_read_b128 v[140:143], v197 offset:43520
	ds_read_b128 v[144:147], v197 offset:47872
	s_waitcnt lgkmcnt(0)
	v_mfma_f32_16x16x32_bf16 v[32:35], v[132:135], v[100:103], 0
	v_mfma_f32_16x16x32_bf16 v[36:39], v[136:139], v[100:103], 0
	v_mfma_f32_16x16x32_bf16 v[40:43], v[140:143], v[100:103], 0
	v_mfma_f32_16x16x32_bf16 v[44:47], v[144:147], v[100:103], 0
	s_cmp_lt_u32 s2, 2
	s_cbranch_scc1 .Lm1c_g2_done
	ds_read_b128 v[132:135], v197 offset:34880
	ds_read_b128 v[136:139], v197 offset:39232
	ds_read_b128 v[140:143], v197 offset:43584
	ds_read_b128 v[144:147], v197 offset:47936
	s_waitcnt lgkmcnt(0)
	v_mfma_f32_16x16x32_bf16 v[32:35], v[132:135], v[104:107], v[32:35]
	v_mfma_f32_16x16x32_bf16 v[36:39], v[136:139], v[104:107], v[36:39]
	v_mfma_f32_16x16x32_bf16 v[40:43], v[140:143], v[104:107], v[40:43]
	v_mfma_f32_16x16x32_bf16 v[44:47], v[144:147], v[104:107], v[44:47]
	s_cmp_lt_u32 s2, 4
	s_cbranch_scc1 .Lm1c_g2_done
	ds_read_b128 v[132:135], v197 offset:34944
	ds_read_b128 v[136:139], v197 offset:39296
	ds_read_b128 v[140:143], v197 offset:43648
	ds_read_b128 v[144:147], v197 offset:48000
	s_waitcnt lgkmcnt(0)
	v_mfma_f32_16x16x32_bf16 v[32:35], v[132:135], v[108:111], v[32:35]
	v_mfma_f32_16x16x32_bf16 v[36:39], v[136:139], v[108:111], v[36:39]
	v_mfma_f32_16x16x32_bf16 v[40:43], v[140:143], v[108:111], v[40:43]
	v_mfma_f32_16x16x32_bf16 v[44:47], v[144:147], v[108:111], v[44:47]
	s_cmp_lt_u32 s2, 6
	s_cbranch_scc1 .Lm1c_g2_done
	ds_read_b128 v[132:135], v197 offset:35008
	ds_read_b128 v[136:139], v197 offset:39360
	ds_read_b128 v[140:143], v197 offset:43712
	ds_read_b128 v[144:147], v197 offset:48064
	s_waitcnt lgkmcnt(0)
	v_mfma_f32_16x16x32_bf16 v[32:35], v[132:135], v[112:115], v[32:35]
	v_mfma_f32_16x16x32_bf16 v[36:39], v[136:139], v[112:115], v[36:39]
	v_mfma_f32_16x16x32_bf16 v[40:43], v[140:143], v[112:115], v[40:43]
	v_mfma_f32_16x16x32_bf16 v[44:47], v[144:147], v[112:115], v[44:47]
.Lm1c_g2_done:
	ds_read_b128 v[132:135], v197 offset:52224
	ds_read_b128 v[136:139], v197 offset:56576
	ds_read_b128 v[140:143], v197 offset:60928
	ds_read_b128 v[144:147], v197 offset:65280
	s_waitcnt lgkmcnt(0)
	v_mfma_f32_16x16x32_bf16 v[48:51], v[132:135], v[116:119], 0
	v_mfma_f32_16x16x32_bf16 v[52:55], v[136:139], v[116:119], 0
	v_mfma_f32_16x16x32_bf16 v[56:59], v[140:143], v[116:119], 0
	v_mfma_f32_16x16x32_bf16 v[60:63], v[144:147], v[116:119], 0
	s_cmp_lt_u32 s2, 2
	s_cbranch_scc1 .Lm1c_g3_done
	ds_read_b128 v[132:135], v197 offset:52288
	ds_read_b128 v[136:139], v197 offset:56640
	ds_read_b128 v[140:143], v197 offset:60992
	ds_read_b128 v[144:147], v197 offset:65344
	s_waitcnt lgkmcnt(0)
	v_mfma_f32_16x16x32_bf16 v[48:51], v[132:135], v[120:123], v[48:51]
	v_mfma_f32_16x16x32_bf16 v[52:55], v[136:139], v[120:123], v[52:55]
	v_mfma_f32_16x16x32_bf16 v[56:59], v[140:143], v[120:123], v[56:59]
	v_mfma_f32_16x16x32_bf16 v[60:63], v[144:147], v[120:123], v[60:63]
	s_cmp_lt_u32 s2, 4
	s_cbranch_scc1 .Lm1c_g3_done
	ds_read_b128 v[132:135], v197 offset:52352
	ds_read_b128 v[136:139], v197 offset:56704
	ds_read_b128 v[140:143], v197 offset:61056
	ds_read_b128 v[144:147], v197 offset:65408
	s_waitcnt lgkmcnt(0)
	v_mfma_f32_16x16x32_bf16 v[48:51], v[132:135], v[124:127], v[48:51]
	v_mfma_f32_16x16x32_bf16 v[52:55], v[136:139], v[124:127], v[52:55]
	v_mfma_f32_16x16x32_bf16 v[56:59], v[140:143], v[124:127], v[56:59]
	v_mfma_f32_16x16x32_bf16 v[60:63], v[144:147], v[124:127], v[60:63]
	s_cmp_lt_u32 s2, 6
	s_cbranch_scc1 .Lm1c_g3_done
	ds_read_b128 v[132:135], v197 offset:52416
	ds_read_b128 v[136:139], v197 offset:56768
	ds_read_b128 v[140:143], v197 offset:61120
	ds_read_b128 v[144:147], v197 offset:65472
	s_waitcnt lgkmcnt(0)
	v_mfma_f32_16x16x32_bf16 v[48:51], v[132:135], v[128:131], v[48:51]
	v_mfma_f32_16x16x32_bf16 v[52:55], v[136:139], v[128:131], v[52:55]
	v_mfma_f32_16x16x32_bf16 v[56:59], v[140:143], v[128:131], v[56:59]
	v_mfma_f32_16x16x32_bf16 v[60:63], v[144:147], v[128:131], v[60:63]
.Lm1c_g3_done:
	s_nop 7
	s_nop 3
	v_lshlrev_b32_e32 v132, 16, v148
	v_and_b32_e32 v133, 0xffff0000, v148
	v_lshlrev_b32_e32 v134, 16, v149
	v_and_b32_e32 v135, 0xffff0000, v149
	v_mul_f32_e32 v136, v132, v132
	v_mul_f32_e32 v137, v133, v133
	v_mul_f32_e32 v138, v134, v134
	v_mul_f32_e32 v139, v135, v135
	v_fma_f32 v136, v136, v191, v190
	v_fma_f32 v137, v137, v191, v190
	v_fma_f32 v138, v138, v191, v190
	v_fma_f32 v139, v139, v191, v190
	v_mul_f32_e32 v136, v136, v132
	v_mul_f32_e32 v137, v137, v133
	v_mul_f32_e32 v138, v138, v134
	v_mul_f32_e32 v139, v139, v135
	v_exp_f32_e32 v136, v136
	v_exp_f32_e32 v137, v137
	v_exp_f32_e32 v138, v138
	v_exp_f32_e32 v139, v139
	s_nop 0
	v_add_f32_e32 v136, 1.0, v136
	v_add_f32_e32 v137, 1.0, v137
	v_add_f32_e32 v138, 1.0, v138
	v_add_f32_e32 v139, 1.0, v139
	v_rcp_f32_e32 v136, v136
	v_rcp_f32_e32 v137, v137
	v_rcp_f32_e32 v138, v138
	v_rcp_f32_e32 v139, v139
	s_nop 0
	v_mul_f32_e32 v132, v132, v136
	v_mul_f32_e32 v133, v133, v137
	v_mul_f32_e32 v134, v134, v138
	v_mul_f32_e32 v135, v135, v139
	v_add_f32_e32 v0, v0, v180
	v_add_f32_e32 v1, v1, v180
	v_add_f32_e32 v2, v2, v180
	v_add_f32_e32 v3, v3, v180
	v_mul_f32_e32 v0, v132, v0
	v_mul_f32_e32 v1, v133, v1
	v_mul_f32_e32 v2, v134, v2
	v_mul_f32_e32 v3, v135, v3
	v_mul_f32_e32 v140, v0, v0
	v_fmac_f32_e32 v140, v1, v1
	v_fmac_f32_e32 v140, v2, v2
	v_fmac_f32_e32 v140, v3, v3
	v_lshlrev_b32_e32 v132, 16, v150
	v_and_b32_e32 v133, 0xffff0000, v150
	v_lshlrev_b32_e32 v134, 16, v151
	v_and_b32_e32 v135, 0xffff0000, v151
	v_mul_f32_e32 v136, v132, v132
; DI float bf2f(unsigned short b) { return __uint_as_float((unsigned)b << 16); }
; DI float gelu_f(float x) { return x * __builtin_amdgcn_rcpf(1.f + __builtin_amdgcn_exp2f(x * (-2.302208198f + -0.102943240f * (x * x)))); }
; __global__ void __launch_bounds__(512, 2) fwd_megakernel(Args args) {
;     ...
;                         for (int j = 0; j < 4; ++j) {
;                             const int t = 16 * wave + q4 * 4 + j; const float bs = args.in[19][(layer * 4 + gi) * 128 + t];
; #pragma unroll
;                             for (int dt = 0; dt < 4; ++dt) {
;                                 const float uu = gelu_f(bf2f(Us[t * 264 + gi * 64 + 16 * dt + r16]));
;                                 const float o = uu * (acc[dt][j] + bs); ss[j] += o * o; og[gi][dt][j] = o;
;                             }
;                         }
	v_mul_f32_e32 v137, v133, v133
	v_mul_f32_e32 v138, v134, v134
	v_mul_f32_e32 v139, v135, v135
	v_fma_f32 v136, v136, v191, v190
	v_fma_f32 v137, v137, v191, v190
	v_fma_f32 v138, v138, v191, v190
	v_fma_f32 v139, v139, v191, v190
	v_mul_f32_e32 v136, v136, v132
	v_mul_f32_e32 v137, v137, v133
	v_mul_f32_e32 v138, v138, v134
	v_mul_f32_e32 v139, v139, v135
	v_exp_f32_e32 v136, v136
	v_exp_f32_e32 v137, v137
	v_exp_f32_e32 v138, v138
	v_exp_f32_e32 v139, v139
	s_nop 0
	v_add_f32_e32 v136, 1.0, v136
	v_add_f32_e32 v137, 1.0, v137
	v_add_f32_e32 v138, 1.0, v138
	v_add_f32_e32 v139, 1.0, v139
	v_rcp_f32_e32 v136, v136
	v_rcp_f32_e32 v137, v137
	v_rcp_f32_e32 v138, v138
	v_rcp_f32_e32 v139, v139
	s_nop 0
	v_mul_f32_e32 v132, v132, v136
	v_mul_f32_e32 v133, v133, v137
	v_mul_f32_e32 v134, v134, v138
	v_mul_f32_e32 v135, v135, v139
	v_add_f32_e32 v4, v4, v180
	v_add_f32_e32 v5, v5, v180
	v_add_f32_e32 v6, v6, v180
	v_add_f32_e32 v7, v7, v180
	v_mul_f32_e32 v4, v132, v4
	v_mul_f32_e32 v5, v133, v5
	v_mul_f32_e32 v6, v134, v6
	v_mul_f32_e32 v7, v135, v7
	v_fmac_f32_e32 v140, v4, v4
	v_fmac_f32_e32 v140, v5, v5
	v_fmac_f32_e32 v140, v6, v6
	v_fmac_f32_e32 v140, v7, v7
	v_lshlrev_b32_e32 v132, 16, v152
	v_and_b32_e32 v133, 0xffff0000, v152
	v_lshlrev_b32_e32 v134, 16, v153
	v_and_b32_e32 v135, 0xffff0000, v153
	v_mul_f32_e32 v136, v132, v132
	v_mul_f32_e32 v137, v133, v133
	v_mul_f32_e32 v138, v134, v134
	v_mul_f32_e32 v139, v135, v135
	v_fma_f32 v136, v136, v191, v190
	v_fma_f32 v137, v137, v191, v190
	v_fma_f32 v138, v138, v191, v190
	v_fma_f32 v139, v139, v191, v190
	v_mul_f32_e32 v136, v136, v132
	v_mul_f32_e32 v137, v137, v133
	v_mul_f32_e32 v138, v138, v134
	v_mul_f32_e32 v139, v139, v135
	v_exp_f32_e32 v136, v136
	v_exp_f32_e32 v137, v137
	v_exp_f32_e32 v138, v138
	v_exp_f32_e32 v139, v139
	s_nop 0
	v_add_f32_e32 v136, 1.0, v136
	v_add_f32_e32 v137, 1.0, v137
	v_add_f32_e32 v138, 1.0, v138
	v_add_f32_e32 v139, 1.0, v139
	v_rcp_f32_e32 v136, v136
	v_rcp_f32_e32 v137, v137
	v_rcp_f32_e32 v138, v138
	v_rcp_f32_e32 v139, v139
	s_nop 0
	v_mul_f32_e32 v132, v132, v136
	v_mul_f32_e32 v133, v133, v137
	v_mul_f32_e32 v134, v134, v138
	v_mul_f32_e32 v135, v135, v139
	v_add_f32_e32 v8, v8, v180
	v_add_f32_e32 v9, v9, v180
	v_add_f32_e32 v10, v10, v180
	v_add_f32_e32 v11, v11, v180
	v_mul_f32_e32 v8, v132, v8
	v_mul_f32_e32 v9, v133, v9
	v_mul_f32_e32 v10, v134, v10
	v_mul_f32_e32 v11, v135, v11
	v_fmac_f32_e32 v140, v8, v8
	v_fmac_f32_e32 v140, v9, v9
	v_fmac_f32_e32 v140, v10, v10
	v_fmac_f32_e32 v140, v11, v11
	v_lshlrev_b32_e32 v132, 16, v154
	v_and_b32_e32 v133, 0xffff0000, v154
	v_lshlrev_b32_e32 v134, 16, v155
	v_and_b32_e32 v135, 0xffff0000, v155
	v_mul_f32_e32 v136, v132, v132
	v_mul_f32_e32 v137, v133, v133
	v_mul_f32_e32 v138, v134, v134
	v_mul_f32_e32 v139, v135, v135
	v_fma_f32 v136, v136, v191, v190
	v_fma_f32 v137, v137, v191, v190
	v_fma_f32 v138, v138, v191, v190
	v_fma_f32 v139, v139, v191, v190
	v_mul_f32_e32 v136, v136, v132
	v_mul_f32_e32 v137, v137, v133
	v_mul_f32_e32 v138, v138, v134
	v_mul_f32_e32 v139, v139, v135
	v_exp_f32_e32 v136, v136
	v_exp_f32_e32 v137, v137
	v_exp_f32_e32 v138, v138
	v_exp_f32_e32 v139, v139
	s_nop 0
	v_add_f32_e32 v136, 1.0, v136
	v_add_f32_e32 v137, 1.0, v137
	v_add_f32_e32 v138, 1.0, v138
	v_add_f32_e32 v139, 1.0, v139
	v_rcp_f32_e32 v136, v136
	v_rcp_f32_e32 v137, v137
	v_rcp_f32_e32 v138, v138
	v_rcp_f32_e32 v139, v139
	s_nop 0
	v_mul_f32_e32 v132, v132, v136
	v_mul_f32_e32 v133, v133, v137
	v_mul_f32_e32 v134, v134, v138
	v_mul_f32_e32 v135, v135, v139
	v_add_f32_e32 v12, v12, v180
	v_add_f32_e32 v13, v13, v180
	v_add_f32_e32 v14, v14, v180
	v_add_f32_e32 v15, v15, v180
	v_mul_f32_e32 v12, v132, v12
	v_mul_f32_e32 v13, v133, v13
	v_mul_f32_e32 v14, v134, v14
	v_mul_f32_e32 v15, v135, v15
	v_fmac_f32_e32 v140, v12, v12
	v_fmac_f32_e32 v140, v13, v13
	v_fmac_f32_e32 v140, v14, v14
	v_fmac_f32_e32 v140, v15, v15
	v_lshlrev_b32_e32 v132, 16, v156
	v_and_b32_e32 v133, 0xffff0000, v156
	v_lshlrev_b32_e32 v134, 16, v157
	v_and_b32_e32 v135, 0xffff0000, v157
	v_mul_f32_e32 v136, v132, v132
	v_mul_f32_e32 v137, v133, v133
	v_mul_f32_e32 v138, v134, v134
	v_mul_f32_e32 v139, v135, v135
	v_fma_f32 v136, v136, v191, v190
	v_fma_f32 v137, v137, v191, v190
	v_fma_f32 v138, v138, v191, v190
	v_fma_f32 v139, v139, v191, v190
	v_mul_f32_e32 v136, v136, v132
	v_mul_f32_e32 v137, v137, v133
	v_mul_f32_e32 v138, v138, v134
	v_mul_f32_e32 v139, v139, v135
	v_exp_f32_e32 v136, v136
	v_exp_f32_e32 v137, v137
	v_exp_f32_e32 v138, v138
	v_exp_f32_e32 v139, v139
	s_nop 0
	v_add_f32_e32 v136, 1.0, v136
	v_add_f32_e32 v137, 1.0, v137
	v_add_f32_e32 v138, 1.0, v138
	v_add_f32_e32 v139, 1.0, v139
	v_rcp_f32_e32 v136, v136
	v_rcp_f32_e32 v137, v137
	v_rcp_f32_e32 v138, v138
	v_rcp_f32_e32 v139, v139
	s_nop 0
	v_mul_f32_e32 v132, v132, v136
	v_mul_f32_e32 v133, v133, v137
	v_mul_f32_e32 v134, v134, v138
	v_mul_f32_e32 v135, v135, v139
	v_add_f32_e32 v16, v16, v181
	v_add_f32_e32 v17, v17, v181
	v_add_f32_e32 v18, v18, v181
	v_add_f32_e32 v19, v19, v181
	v_mul_f32_e32 v16, v132, v16
	v_mul_f32_e32 v17, v133, v17
	v_mul_f32_e32 v18, v134, v18
	v_mul_f32_e32 v19, v135, v19
	v_fmac_f32_e32 v140, v16, v16
	v_fmac_f32_e32 v140, v17, v17
	v_fmac_f32_e32 v140, v18, v18
	v_fmac_f32_e32 v140, v19, v19
	v_lshlrev_b32_e32 v132, 16, v158
	v_and_b32_e32 v133, 0xffff0000, v158
	v_lshlrev_b32_e32 v134, 16, v159
	v_and_b32_e32 v135, 0xffff0000, v159
	v_mul_f32_e32 v136, v132, v132
	v_mul_f32_e32 v137, v133, v133
	v_mul_f32_e32 v138, v134, v134
	v_mul_f32_e32 v139, v135, v135
	v_fma_f32 v136, v136, v191, v190
	v_fma_f32 v137, v137, v191, v190
; DI float bf2f(unsigned short b) { return __uint_as_float((unsigned)b << 16); }
; DI float gelu_f(float x) { return x * __builtin_amdgcn_rcpf(1.f + __builtin_amdgcn_exp2f(x * (-2.302208198f + -0.102943240f * (x * x)))); }
; __global__ void __launch_bounds__(512, 2) fwd_megakernel(Args args) {
;     ...
;                         for (int j = 0; j < 4; ++j) {
;                             const int t = 16 * wave + q4 * 4 + j; const float bs = args.in[19][(layer * 4 + gi) * 128 + t];
; #pragma unroll
;                             for (int dt = 0; dt < 4; ++dt) {
;                                 const float uu = gelu_f(bf2f(Us[t * 264 + gi * 64 + 16 * dt + r16]));
;                                 const float o = uu * (acc[dt][j] + bs); ss[j] += o * o; og[gi][dt][j] = o;
;                             }
;                         }
	v_fma_f32 v138, v138, v191, v190
	v_fma_f32 v139, v139, v191, v190
	v_mul_f32_e32 v136, v136, v132
	v_mul_f32_e32 v137, v137, v133
	v_mul_f32_e32 v138, v138, v134
	v_mul_f32_e32 v139, v139, v135
	v_exp_f32_e32 v136, v136
	v_exp_f32_e32 v137, v137
	v_exp_f32_e32 v138, v138
	v_exp_f32_e32 v139, v139
	s_nop 0
	v_add_f32_e32 v136, 1.0, v136
	v_add_f32_e32 v137, 1.0, v137
	v_add_f32_e32 v138, 1.0, v138
	v_add_f32_e32 v139, 1.0, v139
	v_rcp_f32_e32 v136, v136
	v_rcp_f32_e32 v137, v137
	v_rcp_f32_e32 v138, v138
	v_rcp_f32_e32 v139, v139
	s_nop 0
	v_mul_f32_e32 v132, v132, v136
	v_mul_f32_e32 v133, v133, v137
	v_mul_f32_e32 v134, v134, v138
	v_mul_f32_e32 v135, v135, v139
	v_add_f32_e32 v20, v20, v181
	v_add_f32_e32 v21, v21, v181
	v_add_f32_e32 v22, v22, v181
	v_add_f32_e32 v23, v23, v181
	v_mul_f32_e32 v20, v132, v20
	v_mul_f32_e32 v21, v133, v21
	v_mul_f32_e32 v22, v134, v22
	v_mul_f32_e32 v23, v135, v23
	v_fmac_f32_e32 v140, v20, v20
	v_fmac_f32_e32 v140, v21, v21
	v_fmac_f32_e32 v140, v22, v22
	v_fmac_f32_e32 v140, v23, v23
	v_lshlrev_b32_e32 v132, 16, v160
	v_and_b32_e32 v133, 0xffff0000, v160
	v_lshlrev_b32_e32 v134, 16, v161
	v_and_b32_e32 v135, 0xffff0000, v161
	v_mul_f32_e32 v136, v132, v132
	v_mul_f32_e32 v137, v133, v133
	v_mul_f32_e32 v138, v134, v134
	v_mul_f32_e32 v139, v135, v135
	v_fma_f32 v136, v136, v191, v190
	v_fma_f32 v137, v137, v191, v190
	v_fma_f32 v138, v138, v191, v190
	v_fma_f32 v139, v139, v191, v190
	v_mul_f32_e32 v136, v136, v132
	v_mul_f32_e32 v137, v137, v133
	v_mul_f32_e32 v138, v138, v134
	v_mul_f32_e32 v139, v139, v135
	v_exp_f32_e32 v136, v136
	v_exp_f32_e32 v137, v137
	v_exp_f32_e32 v138, v138
	v_exp_f32_e32 v139, v139
	s_nop 0
	v_add_f32_e32 v136, 1.0, v136
	v_add_f32_e32 v137, 1.0, v137
	v_add_f32_e32 v138, 1.0, v138
	v_add_f32_e32 v139, 1.0, v139
	v_rcp_f32_e32 v136, v136
	v_rcp_f32_e32 v137, v137
	v_rcp_f32_e32 v138, v138
	v_rcp_f32_e32 v139, v139
	s_nop 0
	v_mul_f32_e32 v132, v132, v136
	v_mul_f32_e32 v133, v133, v137
	v_mul_f32_e32 v134, v134, v138
	v_mul_f32_e32 v135, v135, v139
	v_add_f32_e32 v24, v24, v181
	v_add_f32_e32 v25, v25, v181
	v_add_f32_e32 v26, v26, v181
	v_add_f32_e32 v27, v27, v181
	v_mul_f32_e32 v24, v132, v24
	v_mul_f32_e32 v25, v133, v25
	v_mul_f32_e32 v26, v134, v26
	v_mul_f32_e32 v27, v135, v27
	v_fmac_f32_e32 v140, v24, v24
	v_fmac_f32_e32 v140, v25, v25
	v_fmac_f32_e32 v140, v26, v26
	v_fmac_f32_e32 v140, v27, v27
	v_lshlrev_b32_e32 v132, 16, v162
	v_and_b32_e32 v133, 0xffff0000, v162
	v_lshlrev_b32_e32 v134, 16, v163
	v_and_b32_e32 v135, 0xffff0000, v163
	v_mul_f32_e32 v136, v132, v132
	v_mul_f32_e32 v137, v133, v133
	v_mul_f32_e32 v138, v134, v134
	v_mul_f32_e32 v139, v135, v135
	v_fma_f32 v136, v136, v191, v190
	v_fma_f32 v137, v137, v191, v190
	v_fma_f32 v138, v138, v191, v190
	v_fma_f32 v139, v139, v191, v190
	v_mul_f32_e32 v136, v136, v132
	v_mul_f32_e32 v137, v137, v133
	v_mul_f32_e32 v138, v138, v134
	v_mul_f32_e32 v139, v139, v135
	v_exp_f32_e32 v136, v136
	v_exp_f32_e32 v137, v137
	v_exp_f32_e32 v138, v138
	v_exp_f32_e32 v139, v139
	s_nop 0
	v_add_f32_e32 v136, 1.0, v136
	v_add_f32_e32 v137, 1.0, v137
	v_add_f32_e32 v138, 1.0, v138
	v_add_f32_e32 v139, 1.0, v139
	v_rcp_f32_e32 v136, v136
	v_rcp_f32_e32 v137, v137
	v_rcp_f32_e32 v138, v138
	v_rcp_f32_e32 v139, v139
	s_nop 0
	v_mul_f32_e32 v132, v132, v136
	v_mul_f32_e32 v133, v133, v137
	v_mul_f32_e32 v134, v134, v138
	v_mul_f32_e32 v135, v135, v139
	v_add_f32_e32 v28, v28, v181
	v_add_f32_e32 v29, v29, v181
	v_add_f32_e32 v30, v30, v181
	v_add_f32_e32 v31, v31, v181
	v_mul_f32_e32 v28, v132, v28
	v_mul_f32_e32 v29, v133, v29
	v_mul_f32_e32 v30, v134, v30
	v_mul_f32_e32 v31, v135, v31
	v_fmac_f32_e32 v140, v28, v28
	v_fmac_f32_e32 v140, v29, v29
	v_fmac_f32_e32 v140, v30, v30
	v_fmac_f32_e32 v140, v31, v31
	v_lshlrev_b32_e32 v132, 16, v164
	v_and_b32_e32 v133, 0xffff0000, v164
	v_lshlrev_b32_e32 v134, 16, v165
	v_and_b32_e32 v135, 0xffff0000, v165
	v_mul_f32_e32 v136, v132, v132
	v_mul_f32_e32 v137, v133, v133
	v_mul_f32_e32 v138, v134, v134
	v_mul_f32_e32 v139, v135, v135
	v_fma_f32 v136, v136, v191, v190
	v_fma_f32 v137, v137, v191, v190
	v_fma_f32 v138, v138, v191, v190
	v_fma_f32 v139, v139, v191, v190
	v_mul_f32_e32 v136, v136, v132
	v_mul_f32_e32 v137, v137, v133
	v_mul_f32_e32 v138, v138, v134
	v_mul_f32_e32 v139, v139, v135
	v_exp_f32_e32 v136, v136
	v_exp_f32_e32 v137, v137
	v_exp_f32_e32 v138, v138
	v_exp_f32_e32 v139, v139
	s_nop 0
	v_add_f32_e32 v136, 1.0, v136
	v_add_f32_e32 v137, 1.0, v137
	v_add_f32_e32 v138, 1.0, v138
	v_add_f32_e32 v139, 1.0, v139
	v_rcp_f32_e32 v136, v136
	v_rcp_f32_e32 v137, v137
	v_rcp_f32_e32 v138, v138
	v_rcp_f32_e32 v139, v139
	s_nop 0
	v_mul_f32_e32 v132, v132, v136
	v_mul_f32_e32 v133, v133, v137
	v_mul_f32_e32 v134, v134, v138
	v_mul_f32_e32 v135, v135, v139
	v_add_f32_e32 v32, v32, v182
	v_add_f32_e32 v33, v33, v182
	v_add_f32_e32 v34, v34, v182
	v_add_f32_e32 v35, v35, v182
	v_mul_f32_e32 v32, v132, v32
	v_mul_f32_e32 v33, v133, v33
	v_mul_f32_e32 v34, v134, v34
	v_mul_f32_e32 v35, v135, v35
	v_fmac_f32_e32 v140, v32, v32
	v_fmac_f32_e32 v140, v33, v33
	v_fmac_f32_e32 v140, v34, v34
	v_fmac_f32_e32 v140, v35, v35
	v_lshlrev_b32_e32 v132, 16, v166
	v_and_b32_e32 v133, 0xffff0000, v166
	v_lshlrev_b32_e32 v134, 16, v167
	v_and_b32_e32 v135, 0xffff0000, v167
	v_mul_f32_e32 v136, v132, v132
	v_mul_f32_e32 v137, v133, v133
	v_mul_f32_e32 v138, v134, v134
	v_mul_f32_e32 v139, v135, v135
	v_fma_f32 v136, v136, v191, v190
	v_fma_f32 v137, v137, v191, v190
	v_fma_f32 v138, v138, v191, v190
	v_fma_f32 v139, v139, v191, v190
	v_mul_f32_e32 v136, v136, v132
	v_mul_f32_e32 v137, v137, v133
; DI float bf2f(unsigned short b) { return __uint_as_float((unsigned)b << 16); }
; DI float gelu_f(float x) { return x * __builtin_amdgcn_rcpf(1.f + __builtin_amdgcn_exp2f(x * (-2.302208198f + -0.102943240f * (x * x)))); }
; __global__ void __launch_bounds__(512, 2) fwd_megakernel(Args args) {
;     ...
;                         for (int j = 0; j < 4; ++j) {
;                             const int t = 16 * wave + q4 * 4 + j; const float bs = args.in[19][(layer * 4 + gi) * 128 + t];
; #pragma unroll
;                             for (int dt = 0; dt < 4; ++dt) {
;                                 const float uu = gelu_f(bf2f(Us[t * 264 + gi * 64 + 16 * dt + r16]));
;                                 const float o = uu * (acc[dt][j] + bs); ss[j] += o * o; og[gi][dt][j] = o;
;                             }
;                         }
	v_mul_f32_e32 v138, v138, v134
	v_mul_f32_e32 v139, v139, v135
	v_exp_f32_e32 v136, v136
	v_exp_f32_e32 v137, v137
	v_exp_f32_e32 v138, v138
	v_exp_f32_e32 v139, v139
	s_nop 0
	v_add_f32_e32 v136, 1.0, v136
	v_add_f32_e32 v137, 1.0, v137
	v_add_f32_e32 v138, 1.0, v138
	v_add_f32_e32 v139, 1.0, v139
	v_rcp_f32_e32 v136, v136
	v_rcp_f32_e32 v137, v137
	v_rcp_f32_e32 v138, v138
	v_rcp_f32_e32 v139, v139
	s_nop 0
	v_mul_f32_e32 v132, v132, v136
	v_mul_f32_e32 v133, v133, v137
	v_mul_f32_e32 v134, v134, v138
	v_mul_f32_e32 v135, v135, v139
	v_add_f32_e32 v36, v36, v182
	v_add_f32_e32 v37, v37, v182
	v_add_f32_e32 v38, v38, v182
	v_add_f32_e32 v39, v39, v182
	v_mul_f32_e32 v36, v132, v36
	v_mul_f32_e32 v37, v133, v37
	v_mul_f32_e32 v38, v134, v38
	v_mul_f32_e32 v39, v135, v39
	v_fmac_f32_e32 v140, v36, v36
	v_fmac_f32_e32 v140, v37, v37
	v_fmac_f32_e32 v140, v38, v38
	v_fmac_f32_e32 v140, v39, v39
	v_lshlrev_b32_e32 v132, 16, v168
	v_and_b32_e32 v133, 0xffff0000, v168
	v_lshlrev_b32_e32 v134, 16, v169
	v_and_b32_e32 v135, 0xffff0000, v169
	v_mul_f32_e32 v136, v132, v132
	v_mul_f32_e32 v137, v133, v133
	v_mul_f32_e32 v138, v134, v134
	v_mul_f32_e32 v139, v135, v135
	v_fma_f32 v136, v136, v191, v190
	v_fma_f32 v137, v137, v191, v190
	v_fma_f32 v138, v138, v191, v190
	v_fma_f32 v139, v139, v191, v190
	v_mul_f32_e32 v136, v136, v132
	v_mul_f32_e32 v137, v137, v133
	v_mul_f32_e32 v138, v138, v134
	v_mul_f32_e32 v139, v139, v135
	v_exp_f32_e32 v136, v136
	v_exp_f32_e32 v137, v137
	v_exp_f32_e32 v138, v138
	v_exp_f32_e32 v139, v139
	s_nop 0
	v_add_f32_e32 v136, 1.0, v136
	v_add_f32_e32 v137, 1.0, v137
	v_add_f32_e32 v138, 1.0, v138
	v_add_f32_e32 v139, 1.0, v139
	v_rcp_f32_e32 v136, v136
	v_rcp_f32_e32 v137, v137
	v_rcp_f32_e32 v138, v138
	v_rcp_f32_e32 v139, v139
	s_nop 0
	v_mul_f32_e32 v132, v132, v136
	v_mul_f32_e32 v133, v133, v137
	v_mul_f32_e32 v134, v134, v138
	v_mul_f32_e32 v135, v135, v139
	v_add_f32_e32 v40, v40, v182
	v_add_f32_e32 v41, v41, v182
	v_add_f32_e32 v42, v42, v182
	v_add_f32_e32 v43, v43, v182
	v_mul_f32_e32 v40, v132, v40
	v_mul_f32_e32 v41, v133, v41
	v_mul_f32_e32 v42, v134, v42
	v_mul_f32_e32 v43, v135, v43
	v_fmac_f32_e32 v140, v40, v40
	v_fmac_f32_e32 v140, v41, v41
	v_fmac_f32_e32 v140, v42, v42
	v_fmac_f32_e32 v140, v43, v43
	v_lshlrev_b32_e32 v132, 16, v170
	v_and_b32_e32 v133, 0xffff0000, v170
	v_lshlrev_b32_e32 v134, 16, v171
	v_and_b32_e32 v135, 0xffff0000, v171
	v_mul_f32_e32 v136, v132, v132
	v_mul_f32_e32 v137, v133, v133
	v_mul_f32_e32 v138, v134, v134
	v_mul_f32_e32 v139, v135, v135
	v_fma_f32 v136, v136, v191, v190
	v_fma_f32 v137, v137, v191, v190
	v_fma_f32 v138, v138, v191, v190
	v_fma_f32 v139, v139, v191, v190
	v_mul_f32_e32 v136, v136, v132
	v_mul_f32_e32 v137, v137, v133
	v_mul_f32_e32 v138, v138, v134
	v_mul_f32_e32 v139, v139, v135
	v_exp_f32_e32 v136, v136
	v_exp_f32_e32 v137, v137
	v_exp_f32_e32 v138, v138
	v_exp_f32_e32 v139, v139
	s_nop 0
	v_add_f32_e32 v136, 1.0, v136
	v_add_f32_e32 v137, 1.0, v137
	v_add_f32_e32 v138, 1.0, v138
	v_add_f32_e32 v139, 1.0, v139
	v_rcp_f32_e32 v136, v136
	v_rcp_f32_e32 v137, v137
	v_rcp_f32_e32 v138, v138
	v_rcp_f32_e32 v139, v139
	s_nop 0
	v_mul_f32_e32 v132, v132, v136
	v_mul_f32_e32 v133, v133, v137
	v_mul_f32_e32 v134, v134, v138
	v_mul_f32_e32 v135, v135, v139
	v_add_f32_e32 v44, v44, v182
	v_add_f32_e32 v45, v45, v182
	v_add_f32_e32 v46, v46, v182
	v_add_f32_e32 v47, v47, v182
	v_mul_f32_e32 v44, v132, v44
	v_mul_f32_e32 v45, v133, v45
	v_mul_f32_e32 v46, v134, v46
	v_mul_f32_e32 v47, v135, v47
	v_fmac_f32_e32 v140, v44, v44
	v_fmac_f32_e32 v140, v45, v45
	v_fmac_f32_e32 v140, v46, v46
	v_fmac_f32_e32 v140, v47, v47
	v_lshlrev_b32_e32 v132, 16, v172
	v_and_b32_e32 v133, 0xffff0000, v172
	v_lshlrev_b32_e32 v134, 16, v173
	v_and_b32_e32 v135, 0xffff0000, v173
	v_mul_f32_e32 v136, v132, v132
	v_mul_f32_e32 v137, v133, v133
	v_mul_f32_e32 v138, v134, v134
	v_mul_f32_e32 v139, v135, v135
	v_fma_f32 v136, v136, v191, v190
	v_fma_f32 v137, v137, v191, v190
	v_fma_f32 v138, v138, v191, v190
	v_fma_f32 v139, v139, v191, v190
	v_mul_f32_e32 v136, v136, v132
	v_mul_f32_e32 v137, v137, v133
	v_mul_f32_e32 v138, v138, v134
	v_mul_f32_e32 v139, v139, v135
	v_exp_f32_e32 v136, v136
	v_exp_f32_e32 v137, v137
	v_exp_f32_e32 v138, v138
	v_exp_f32_e32 v139, v139
	s_nop 0
	v_add_f32_e32 v136, 1.0, v136
	v_add_f32_e32 v137, 1.0, v137
	v_add_f32_e32 v138, 1.0, v138
	v_add_f32_e32 v139, 1.0, v139
	v_rcp_f32_e32 v136, v136
	v_rcp_f32_e32 v137, v137
	v_rcp_f32_e32 v138, v138
	v_rcp_f32_e32 v139, v139
	s_nop 0
	v_mul_f32_e32 v132, v132, v136
	v_mul_f32_e32 v133, v133, v137
	v_mul_f32_e32 v134, v134, v138
	v_mul_f32_e32 v135, v135, v139
	v_add_f32_e32 v48, v48, v183
	v_add_f32_e32 v49, v49, v183
	v_add_f32_e32 v50, v50, v183
	v_add_f32_e32 v51, v51, v183
	v_mul_f32_e32 v48, v132, v48
	v_mul_f32_e32 v49, v133, v49
	v_mul_f32_e32 v50, v134, v50
	v_mul_f32_e32 v51, v135, v51
	v_fmac_f32_e32 v140, v48, v48
	v_fmac_f32_e32 v140, v49, v49
	v_fmac_f32_e32 v140, v50, v50
	v_fmac_f32_e32 v140, v51, v51
	v_lshlrev_b32_e32 v132, 16, v174
	v_and_b32_e32 v133, 0xffff0000, v174
	v_lshlrev_b32_e32 v134, 16, v175
	v_and_b32_e32 v135, 0xffff0000, v175
	v_mul_f32_e32 v136, v132, v132
	v_mul_f32_e32 v137, v133, v133
	v_mul_f32_e32 v138, v134, v134
	v_mul_f32_e32 v139, v135, v135
	v_fma_f32 v136, v136, v191, v190
	v_fma_f32 v137, v137, v191, v190
	v_fma_f32 v138, v138, v191, v190
	v_fma_f32 v139, v139, v191, v190
	v_mul_f32_e32 v136, v136, v132
	v_mul_f32_e32 v137, v137, v133
	v_mul_f32_e32 v138, v138, v134
	v_mul_f32_e32 v139, v139, v135
	v_exp_f32_e32 v136, v136
	v_exp_f32_e32 v137, v137
; DI float bf2f(unsigned short b) { return __uint_as_float((unsigned)b << 16); }
; DI float gelu_f(float x) { return x * __builtin_amdgcn_rcpf(1.f + __builtin_amdgcn_exp2f(x * (-2.302208198f + -0.102943240f * (x * x)))); }
; DI float sum16(float v) { v += __shfl_xor(v, 1); v += __shfl_xor(v, 2); v += __shfl_xor(v, 4); v += __shfl_xor(v, 8); return v; }
; __global__ void __launch_bounds__(512, 2) fwd_megakernel(Args args) {
;     ...
;                         for (int j = 0; j < 4; ++j) {
;                             const int t = 16 * wave + q4 * 4 + j; const float bs = args.in[19][(layer * 4 + gi) * 128 + t];
; #pragma unroll
;                             for (int dt = 0; dt < 4; ++dt) {
;                                 const float uu = gelu_f(bf2f(Us[t * 264 + gi * 64 + 16 * dt + r16]));
;                                 const float o = uu * (acc[dt][j] + bs); ss[j] += o * o; og[gi][dt][j] = o;
;                             }
;                         }
;                     }
;                     float rs[4];
; #pragma unroll
;                     for (int j = 0; j < 4; ++j) rs[j] = rsqrtf(sum16(ss[j]) * (1.f / 256.f) + EPS);
; #pragma unroll
;                     for (int gi = 0; gi < 4; ++gi)
; #pragma unroll
;                         for (int dt = 0; dt < 4; ++dt) {
;                             const int col = gi * 64 + 16 * dt + r16; const float nw = args.in[20][layer * 256 + col];
	v_exp_f32_e32 v138, v138
	v_exp_f32_e32 v139, v139
	s_nop 0
	v_add_f32_e32 v136, 1.0, v136
	v_add_f32_e32 v137, 1.0, v137
	v_add_f32_e32 v138, 1.0, v138
	v_add_f32_e32 v139, 1.0, v139
	v_rcp_f32_e32 v136, v136
	v_rcp_f32_e32 v137, v137
	v_rcp_f32_e32 v138, v138
	v_rcp_f32_e32 v139, v139
	s_nop 0
	v_mul_f32_e32 v132, v132, v136
	v_mul_f32_e32 v133, v133, v137
	v_mul_f32_e32 v134, v134, v138
	v_mul_f32_e32 v135, v135, v139
	v_add_f32_e32 v52, v52, v183
	v_add_f32_e32 v53, v53, v183
	v_add_f32_e32 v54, v54, v183
	v_add_f32_e32 v55, v55, v183
	v_mul_f32_e32 v52, v132, v52
	v_mul_f32_e32 v53, v133, v53
	v_mul_f32_e32 v54, v134, v54
	v_mul_f32_e32 v55, v135, v55
	v_fmac_f32_e32 v140, v52, v52
	v_fmac_f32_e32 v140, v53, v53
	v_fmac_f32_e32 v140, v54, v54
	v_fmac_f32_e32 v140, v55, v55
	v_lshlrev_b32_e32 v132, 16, v176
	v_and_b32_e32 v133, 0xffff0000, v176
	v_lshlrev_b32_e32 v134, 16, v177
	v_and_b32_e32 v135, 0xffff0000, v177
	v_mul_f32_e32 v136, v132, v132
	v_mul_f32_e32 v137, v133, v133
	v_mul_f32_e32 v138, v134, v134
	v_mul_f32_e32 v139, v135, v135
	v_fma_f32 v136, v136, v191, v190
	v_fma_f32 v137, v137, v191, v190
	v_fma_f32 v138, v138, v191, v190
	v_fma_f32 v139, v139, v191, v190
	v_mul_f32_e32 v136, v136, v132
	v_mul_f32_e32 v137, v137, v133
	v_mul_f32_e32 v138, v138, v134
	v_mul_f32_e32 v139, v139, v135
	v_exp_f32_e32 v136, v136
	v_exp_f32_e32 v137, v137
	v_exp_f32_e32 v138, v138
	v_exp_f32_e32 v139, v139
	s_nop 0
	v_add_f32_e32 v136, 1.0, v136
	v_add_f32_e32 v137, 1.0, v137
	v_add_f32_e32 v138, 1.0, v138
	v_add_f32_e32 v139, 1.0, v139
	v_rcp_f32_e32 v136, v136
	v_rcp_f32_e32 v137, v137
	v_rcp_f32_e32 v138, v138
	v_rcp_f32_e32 v139, v139
	s_nop 0
	v_mul_f32_e32 v132, v132, v136
	v_mul_f32_e32 v133, v133, v137
	v_mul_f32_e32 v134, v134, v138
	v_mul_f32_e32 v135, v135, v139
	v_add_f32_e32 v56, v56, v183
	v_add_f32_e32 v57, v57, v183
	v_add_f32_e32 v58, v58, v183
	v_add_f32_e32 v59, v59, v183
	v_mul_f32_e32 v56, v132, v56
	v_mul_f32_e32 v57, v133, v57
	v_mul_f32_e32 v58, v134, v58
	v_mul_f32_e32 v59, v135, v59
	v_fmac_f32_e32 v140, v56, v56
	v_fmac_f32_e32 v140, v57, v57
	v_fmac_f32_e32 v140, v58, v58
	v_fmac_f32_e32 v140, v59, v59
	v_lshlrev_b32_e32 v132, 16, v178
	v_and_b32_e32 v133, 0xffff0000, v178
	v_lshlrev_b32_e32 v134, 16, v179
	v_and_b32_e32 v135, 0xffff0000, v179
	v_mul_f32_e32 v136, v132, v132
	v_mul_f32_e32 v137, v133, v133
	v_mul_f32_e32 v138, v134, v134
	v_mul_f32_e32 v139, v135, v135
	v_fma_f32 v136, v136, v191, v190
	v_fma_f32 v137, v137, v191, v190
	v_fma_f32 v138, v138, v191, v190
	v_fma_f32 v139, v139, v191, v190
	v_mul_f32_e32 v136, v136, v132
	v_mul_f32_e32 v137, v137, v133
	v_mul_f32_e32 v138, v138, v134
	v_mul_f32_e32 v139, v139, v135
	v_exp_f32_e32 v136, v136
	v_exp_f32_e32 v137, v137
	v_exp_f32_e32 v138, v138
	v_exp_f32_e32 v139, v139
	s_nop 0
	v_add_f32_e32 v136, 1.0, v136
	v_add_f32_e32 v137, 1.0, v137
	v_add_f32_e32 v138, 1.0, v138
	v_add_f32_e32 v139, 1.0, v139
	v_rcp_f32_e32 v136, v136
	v_rcp_f32_e32 v137, v137
	v_rcp_f32_e32 v138, v138
	v_rcp_f32_e32 v139, v139
	s_nop 0
	v_mul_f32_e32 v132, v132, v136
	v_mul_f32_e32 v133, v133, v137
	v_mul_f32_e32 v134, v134, v138
	v_mul_f32_e32 v135, v135, v139
	v_add_f32_e32 v60, v60, v183
	v_add_f32_e32 v61, v61, v183
	v_add_f32_e32 v62, v62, v183
	v_add_f32_e32 v63, v63, v183
	v_mul_f32_e32 v60, v132, v60
	v_mul_f32_e32 v61, v133, v61
	v_mul_f32_e32 v62, v134, v62
	v_mul_f32_e32 v63, v135, v63
	v_fmac_f32_e32 v140, v60, v60
	v_fmac_f32_e32 v140, v61, v61
	v_fmac_f32_e32 v140, v62, v62
	v_fmac_f32_e32 v140, v63, v63
	v_xor_b32_e32 v141, 16, v184
	v_lshlrev_b32_e32 v141, 2, v141
	v_xor_b32_e32 v142, 32, v184
	v_lshlrev_b32_e32 v142, 2, v142
	ds_bpermute_b32 v143, v141, v140
	v_lshlrev_b32_e32 v188, 4, v186
	global_load_dwordx4 v[64:67], v188, s[24:25] offset:0
	global_load_dwordx4 v[68:71], v188, s[24:25] offset:64
	global_load_dwordx4 v[72:75], v188, s[24:25] offset:128
	global_load_dwordx4 v[76:79], v188, s[24:25] offset:192
	global_load_dwordx4 v[80:83], v188, s[24:25] offset:256
	global_load_dwordx4 v[84:87], v188, s[24:25] offset:320
	global_load_dwordx4 v[92:95], v188, s[24:25] offset:384
	global_load_dwordx4 v[96:99], v188, s[24:25] offset:448
	s_waitcnt lgkmcnt(0)
	v_add_f32_e32 v140, v140, v143
	ds_bpermute_b32 v143, v142, v140
	v_lshlrev_b32_e32 v198, 11, v187
	v_lshl_add_u32 v198, v186, 3, v198
	v_mov_b32_e32 v144, 0x358637bd
	s_waitcnt lgkmcnt(0)
	v_add_f32_e32 v140, v140, v143
	v_fmamk_f32 v140, v140, 0x3b800000, v144
	v_rsq_f32_e32 v144, v140
	s_waitcnt vmcnt(0)
; DI unsigned short f2bf(float f) { return (unsigned short)(pk2(f, 0.f) & 0xffffu); }
; DI float sum16(float v) { v += __shfl_xor(v, 1); v += __shfl_xor(v, 2); v += __shfl_xor(v, 4); v += __shfl_xor(v, 8); return v; }
; __global__ void __launch_bounds__(512, 2) fwd_megakernel(Args args) {
;     ...
;                     for (int j = 0; j < 4; ++j) rs[j] = rsqrtf(sum16(ss[j]) * (1.f / 256.f) + EPS);
; #pragma unroll
;                     for (int gi = 0; gi < 4; ++gi)
; #pragma unroll
;                         for (int dt = 0; dt < 4; ++dt) {
;                             const int col = gi * 64 + 16 * dt + r16; const float nw = args.in[20][layer * 256 + col];
; #pragma unroll
;                             for (int j = 0; j < 4; ++j) ycat[(grow0 + 16 * wave + q4 * 4 + j) * DM + 768 + col] = f2bf(og[gi][dt][j] * rs[j] * nw);
;                         }
;                 }
;                 __syncthreads();
	v_mul_f32_e32 v0, v0, v144
	v_mul_f32_e32 v1, v1, v144
	v_mul_f32_e32 v2, v2, v144
	v_mul_f32_e32 v3, v3, v144
	v_mul_f32_e32 v0, v0, v64
	v_mul_f32_e32 v1, v1, v65
	v_mul_f32_e32 v2, v2, v66
	v_mul_f32_e32 v3, v3, v67
	v_cvt_pk_bf16_f32 v132, v0, v1
	v_cvt_pk_bf16_f32 v133, v2, v3
	global_store_dwordx2 v198, v[132:133], s[10:11] offset:0
	v_mul_f32_e32 v4, v4, v144
	v_mul_f32_e32 v5, v5, v144
	v_mul_f32_e32 v6, v6, v144
	v_mul_f32_e32 v7, v7, v144
	v_mul_f32_e32 v4, v4, v68
	v_mul_f32_e32 v5, v5, v69
	v_mul_f32_e32 v6, v6, v70
	v_mul_f32_e32 v7, v7, v71
	v_cvt_pk_bf16_f32 v132, v4, v5
	v_cvt_pk_bf16_f32 v133, v6, v7
	global_store_dwordx2 v198, v[132:133], s[10:11] offset:32
	v_mul_f32_e32 v8, v8, v144
	v_mul_f32_e32 v9, v9, v144
	v_mul_f32_e32 v10, v10, v144
	v_mul_f32_e32 v11, v11, v144
	v_mul_f32_e32 v8, v8, v72
	v_mul_f32_e32 v9, v9, v73
	v_mul_f32_e32 v10, v10, v74
	v_mul_f32_e32 v11, v11, v75
	v_cvt_pk_bf16_f32 v132, v8, v9
	v_cvt_pk_bf16_f32 v133, v10, v11
	global_store_dwordx2 v198, v[132:133], s[10:11] offset:64
	v_mul_f32_e32 v12, v12, v144
	v_mul_f32_e32 v13, v13, v144
	v_mul_f32_e32 v14, v14, v144
	v_mul_f32_e32 v15, v15, v144
	v_mul_f32_e32 v12, v12, v76
	v_mul_f32_e32 v13, v13, v77
	v_mul_f32_e32 v14, v14, v78
	v_mul_f32_e32 v15, v15, v79
	v_cvt_pk_bf16_f32 v132, v12, v13
	v_cvt_pk_bf16_f32 v133, v14, v15
	global_store_dwordx2 v198, v[132:133], s[10:11] offset:96
	v_mul_f32_e32 v16, v16, v144
	v_mul_f32_e32 v17, v17, v144
	v_mul_f32_e32 v18, v18, v144
	v_mul_f32_e32 v19, v19, v144
	v_mul_f32_e32 v16, v16, v80
	v_mul_f32_e32 v17, v17, v81
	v_mul_f32_e32 v18, v18, v82
	v_mul_f32_e32 v19, v19, v83
	v_cvt_pk_bf16_f32 v132, v16, v17
	v_cvt_pk_bf16_f32 v133, v18, v19
	global_store_dwordx2 v198, v[132:133], s[10:11] offset:128
	v_mul_f32_e32 v20, v20, v144
	v_mul_f32_e32 v21, v21, v144
	v_mul_f32_e32 v22, v22, v144
	v_mul_f32_e32 v23, v23, v144
	v_mul_f32_e32 v20, v20, v84
	v_mul_f32_e32 v21, v21, v85
	v_mul_f32_e32 v22, v22, v86
	v_mul_f32_e32 v23, v23, v87
	v_cvt_pk_bf16_f32 v132, v20, v21
	v_cvt_pk_bf16_f32 v133, v22, v23
	global_store_dwordx2 v198, v[132:133], s[10:11] offset:160
	v_mul_f32_e32 v24, v24, v144
	v_mul_f32_e32 v25, v25, v144
	v_mul_f32_e32 v26, v26, v144
	v_mul_f32_e32 v27, v27, v144
	v_mul_f32_e32 v24, v24, v92
	v_mul_f32_e32 v25, v25, v93
	v_mul_f32_e32 v26, v26, v94
	v_mul_f32_e32 v27, v27, v95
	v_cvt_pk_bf16_f32 v132, v24, v25
	v_cvt_pk_bf16_f32 v133, v26, v27
	global_store_dwordx2 v198, v[132:133], s[10:11] offset:192
	v_mul_f32_e32 v28, v28, v144
	v_mul_f32_e32 v29, v29, v144
	v_mul_f32_e32 v30, v30, v144
	v_mul_f32_e32 v31, v31, v144
	v_mul_f32_e32 v28, v28, v96
	v_mul_f32_e32 v29, v29, v97
	v_mul_f32_e32 v30, v30, v98
	v_mul_f32_e32 v31, v31, v99
	v_cvt_pk_bf16_f32 v132, v28, v29
	v_cvt_pk_bf16_f32 v133, v30, v31
	global_store_dwordx2 v198, v[132:133], s[10:11] offset:224
	global_load_dwordx4 v[64:67], v188, s[24:25] offset:512
	global_load_dwordx4 v[68:71], v188, s[24:25] offset:576
	global_load_dwordx4 v[72:75], v188, s[24:25] offset:640
	global_load_dwordx4 v[76:79], v188, s[24:25] offset:704
	global_load_dwordx4 v[80:83], v188, s[24:25] offset:768
	global_load_dwordx4 v[84:87], v188, s[24:25] offset:832
	global_load_dwordx4 v[92:95], v188, s[24:25] offset:896
	global_load_dwordx4 v[96:99], v188, s[24:25] offset:960
	s_waitcnt vmcnt(0)
	v_mul_f32_e32 v32, v32, v144
	v_mul_f32_e32 v33, v33, v144
	v_mul_f32_e32 v34, v34, v144
	v_mul_f32_e32 v35, v35, v144
	v_mul_f32_e32 v32, v32, v64
	v_mul_f32_e32 v33, v33, v65
	v_mul_f32_e32 v34, v34, v66
	v_mul_f32_e32 v35, v35, v67
	v_cvt_pk_bf16_f32 v132, v32, v33
	v_cvt_pk_bf16_f32 v133, v34, v35
	global_store_dwordx2 v198, v[132:133], s[10:11] offset:256
	v_mul_f32_e32 v36, v36, v144
	v_mul_f32_e32 v37, v37, v144
	v_mul_f32_e32 v38, v38, v144
	v_mul_f32_e32 v39, v39, v144
	v_mul_f32_e32 v36, v36, v68
	v_mul_f32_e32 v37, v37, v69
	v_mul_f32_e32 v38, v38, v70
	v_mul_f32_e32 v39, v39, v71
	v_cvt_pk_bf16_f32 v132, v36, v37
	v_cvt_pk_bf16_f32 v133, v38, v39
	global_store_dwordx2 v198, v[132:133], s[10:11] offset:288
	v_mul_f32_e32 v40, v40, v144
	v_mul_f32_e32 v41, v41, v144
	v_mul_f32_e32 v42, v42, v144
	v_mul_f32_e32 v43, v43, v144
	v_mul_f32_e32 v40, v40, v72
	v_mul_f32_e32 v41, v41, v73
	v_mul_f32_e32 v42, v42, v74
	v_mul_f32_e32 v43, v43, v75
	v_cvt_pk_bf16_f32 v132, v40, v41
	v_cvt_pk_bf16_f32 v133, v42, v43
	global_store_dwordx2 v198, v[132:133], s[10:11] offset:320
	v_mul_f32_e32 v44, v44, v144
	v_mul_f32_e32 v45, v45, v144
	v_mul_f32_e32 v46, v46, v144
	v_mul_f32_e32 v47, v47, v144
	v_mul_f32_e32 v44, v44, v76
	v_mul_f32_e32 v45, v45, v77
	v_mul_f32_e32 v46, v46, v78
	v_mul_f32_e32 v47, v47, v79
	v_cvt_pk_bf16_f32 v132, v44, v45
	v_cvt_pk_bf16_f32 v133, v46, v47
	global_store_dwordx2 v198, v[132:133], s[10:11] offset:352
	v_mul_f32_e32 v48, v48, v144
	v_mul_f32_e32 v49, v49, v144
	v_mul_f32_e32 v50, v50, v144
	v_mul_f32_e32 v51, v51, v144
	v_mul_f32_e32 v48, v48, v80
	v_mul_f32_e32 v49, v49, v81
	v_mul_f32_e32 v50, v50, v82
	v_mul_f32_e32 v51, v51, v83
	v_cvt_pk_bf16_f32 v132, v48, v49
	v_cvt_pk_bf16_f32 v133, v50, v51
	global_store_dwordx2 v198, v[132:133], s[10:11] offset:384
	v_mul_f32_e32 v52, v52, v144
	v_mul_f32_e32 v53, v53, v144
	v_mul_f32_e32 v54, v54, v144
	v_mul_f32_e32 v55, v55, v144
	v_mul_f32_e32 v52, v52, v84
	v_mul_f32_e32 v53, v53, v85
	v_mul_f32_e32 v54, v54, v86
	v_mul_f32_e32 v55, v55, v87
	v_cvt_pk_bf16_f32 v132, v52, v53
	v_cvt_pk_bf16_f32 v133, v54, v55
	global_store_dwordx2 v198, v[132:133], s[10:11] offset:416
	v_mul_f32_e32 v56, v56, v144
	v_mul_f32_e32 v57, v57, v144
	v_mul_f32_e32 v58, v58, v144
	v_mul_f32_e32 v59, v59, v144
	v_mul_f32_e32 v56, v56, v92
	v_mul_f32_e32 v57, v57, v93
	v_mul_f32_e32 v58, v58, v94
	v_mul_f32_e32 v59, v59, v95
	v_cvt_pk_bf16_f32 v132, v56, v57
	v_cvt_pk_bf16_f32 v133, v58, v59
	global_store_dwordx2 v198, v[132:133], s[10:11] offset:448
	v_mul_f32_e32 v60, v60, v144
	v_mul_f32_e32 v61, v61, v144
	v_mul_f32_e32 v62, v62, v144
	v_mul_f32_e32 v63, v63, v144
	v_mul_f32_e32 v60, v60, v96
	v_mul_f32_e32 v61, v61, v97
	v_mul_f32_e32 v62, v62, v98
	v_mul_f32_e32 v63, v63, v99
	v_cvt_pk_bf16_f32 v132, v60, v61
	v_cvt_pk_bf16_f32 v133, v62, v63
	global_store_dwordx2 v198, v[132:133], s[10:11] offset:480
	s_waitcnt lgkmcnt(0)
	s_barrier
	s_branch .LBB0_403

; #define LAS __attribute__((address_space(3)))
; DI unsigned short f2bf(float f) { return (unsigned short)(pk2(f, 0.f) & 0xffffu); }
; __global__ void __launch_bounds__(512, 2) fwd_megakernel(Args args) {
;     ...
;                     __syncthreads();
; #pragma unroll 1
;                     for (int hh = 0; hh < 4; ++hh) {
;                         const int h = g2 * 4 + hh; const int unit8 = ((b * NCH + c) * 8) + h;
;                         bf16x8 pvf[4][4];
;                         {
;                             const bf16* pv = PV + (size_t)unit8 * 8192;
; #pragma unroll
;                             for (int ks = 0; ks < 4; ++ks)
; #pragma unroll
;                                 for (int pt = 0; pt < 4; ++pt) pvf[ks][pt] = *(const bf16x8*)(pv + (16 * pt + r16) * 128 + ks * 32 + q4 * 8);
;                         }
;                         bf16 zr[4][4];
; #pragma unroll
;                         for (int j = 0; j < 4; ++j)
; #pragma unroll
;                             for (int pt = 0; pt < 4; ++pt) zr[j][pt] = proj[(grow0 + 16 * wave + q4 * 4 + j) * NPROJ + PC_Z + h * 64 + 16 * pt + r16];
;                         const LAS float* hdt = s_dt + hh * 128; const LAS float* hacs = s_acs + hh * 128;
;                         float acl[4];
; #pragma unroll
;                         for (int j = 0; j < 4; ++j) acl[j] = hacs[16 * wave + q4 * 4 + j];
; #pragma unroll
;                         for (int st = 0; st < 8; ++st) {
;                             if (st <= (wave | 1)) {
;                                 const int sI = 16 * st + r16; const float acss = hacs[sI], dts = hdt[sI];
; #pragma unroll
;                                 for (int j = 0; j < 4; ++j) { const int l = 16 * wave + q4 * 4 + j; const float mv = (sI <= l) ? cbr[st][j] * __expf(fminf(acl[j] - acss, 0.f)) * dts : 0.f; Ms[l * 136 + sI] = f2bf(mv); }
;                             }
;                         }
.Lm3_cb_done:
	s_waitcnt lgkmcnt(0)
	s_barrier
	s_waitcnt vmcnt(0)
	ds_write_b128 v183, v[196:199]
	ds_write_b128 v183, v[234:237] offset:1088
	s_waitcnt lgkmcnt(0)
	s_mov_b32 s28, 0
	s_mov_b32 s3, 0
